# MLA loop: second max chain interleaved with the PV MFMAs, pointer bumps behind the 6th QK MFMA
# speedup vs baseline: 1.0067x; 1.0019x over previous
; __device__ __forceinline__ void finishSM9(f32x16& p0, f32x16& p1, float alpha, float& l_reg, v8i32& p8) {
; #pragma unroll
;   for (int r = 0; r < 16; ++r) { p0[r] = __builtin_amdgcn_exp2f(p0[r]); p1[r] = __builtin_amdgcn_exp2f(p1[r]); }
;   float ps = 0;
; #pragma unroll
;   for (int r = 0; r < 16; ++r) ps += p0[r];
; #pragma unroll
;   for (int r = 0; r < 16; ++r) ps += p1[r];
;   { auto rr = __builtin_amdgcn_permlane32_swap(__float_as_uint(ps), __float_as_uint(ps), false, false);
;     ps = __uint_as_float(rr[0]) + __uint_as_float(rr[1]); }
;   l_reg = l_reg * alpha + ps;
; #pragma unroll
;   for (int g = 0; g < 4; ++g) {
;     int w = __builtin_amdgcn_cvt_pk_fp8_f32(p0[4 * g], p0[4 * g + 1], 0, false); p8[g] = __builtin_amdgcn_cvt_pk_fp8_f32(p0[4 * g + 2], p0[4 * g + 3], w, true);
;     int u = __builtin_amdgcn_cvt_pk_fp8_f32(p1[4 * g], p1[4 * g + 1], 0, false); p8[4 + g] = __builtin_amdgcn_cvt_pk_fp8_f32(p1[4 * g + 2], p1[4 * g + 3], u, true); }
; }
; __device__ __forceinline__ void pv8(f32x16* o, const char* Vt, const v8i32 p8, int r32, int hi) {
;   const int sw = (r32 >> 2) & 3, a0 = r32 * 64 + (((hi * 2) ^ sw) << 4), a1 = r32 * 64 + (((hi * 2 + 1) ^ sw) << 4);
; #pragma unroll
;   for (int d0 = 0; d0 < 4; ++d0) {
;     const v8i32 vf = cat8(*reinterpret_cast<const v4i32*>(Vt + d0 * 2048 + a0), *reinterpret_cast<const v4i32*>(Vt + d0 * 2048 + a1));
;     o[d0] = __builtin_amdgcn_mfma_scale_f32_32x32x64_f8f6f4(p8, vf, o[d0], 0, 0, 0, 127, 0, 127); }
; }
; __device__ __forceinline__ void qkt9(f32x16& p0, f32x16& p1, const char* Kn, const char* Kr, const v8i32* qf, const float init, int r32, int hi) {
; #pragma unroll
;   for (int r = 0; r < 16; ++r) { p0[r] = init; p1[r] = init; }
; #pragma unroll
;   for (int s = 0; s < 2; ++s) { const int c0 = s * 4 + hi * 2;
;     const v8i32 a0 = cat8(*reinterpret_cast<const v4i32*>(Kn + KN8SW(r32, c0)), *reinterpret_cast<const v4i32*>(Kn + KN8SW(r32, c0 + 1)));
;     const v8i32 a1 = cat8(*reinterpret_cast<const v4i32*>(Kn + 4096 + KN8SW(r32, c0)), *reinterpret_cast<const v4i32*>(Kn + 4096 + KN8SW(r32, c0 + 1)));
;     p0 = __builtin_amdgcn_mfma_scale_f32_32x32x64_f8f6f4(a0, qf[s], p0, 0, 0, 0, 127, 0, 124);
;     p1 = __builtin_amdgcn_mfma_scale_f32_32x32x64_f8f6f4(a1, qf[s], p1, 0, 0, 0, 127, 0, 124); }
;   { const int c0 = hi * 2;
.LBB0_1321:
	global_load_dwordx4 v[158:161], v176, s[18:19]
	global_load_dwordx4 v[162:165], v178, s[16:17]
	global_load_dwordx4 v[154:157], v[180:181], off
	ds_read_b128 v[114:117], v215 offset:24576
	ds_read_b128 v[118:121], v216 offset:24576
	ds_read_b128 v[222:225], v215 offset:28672
	ds_read_b128 v[226:229], v216 offset:28672
	v_exp_f32_e32 v0, v82
	v_exp_f32_e32 v177, v83
	v_exp_f32_e32 v179, v84
	v_exp_f32_e32 v254, v85
	v_add_f32_e32 v219, v0, v177
	v_cvt_pk_fp8_f32 v246, v0, v177
	v_add_f32_e32 v219, v179, v219
	v_add_f32_e32 v219, v254, v219
	v_cvt_pk_fp8_f32 v246, v179, v254 op_sel:[0,0,1]
	s_waitcnt lgkmcnt(2)
	v_mfma_scale_f32_32x32x64_f8f6f4 v[114:129], v[114:121], v[146:153], v[230:245], v194, v193 op_sel_hi:[0,0,0]
	v_exp_f32_e32 v0, v86
	v_exp_f32_e32 v177, v87
	v_exp_f32_e32 v179, v88
	v_exp_f32_e32 v254, v89
	v_add_f32_e32 v219, v0, v219
	v_add_f32_e32 v219, v177, v219
	v_cvt_pk_fp8_f32 v247, v0, v177
	v_add_f32_e32 v219, v179, v219
	v_add_f32_e32 v219, v254, v219
	v_cvt_pk_fp8_f32 v247, v179, v254 op_sel:[0,0,1]
	ds_read_b128 v[82:85], v213 offset:24576
	ds_read_b128 v[86:89], v214 offset:24576
	s_waitcnt lgkmcnt(2)
	v_mfma_scale_f32_32x32x64_f8f6f4 v[98:113], v[222:229], v[146:153], v[230:245], v194, v193 op_sel_hi:[0,0,0]
	ds_read_b128 v[222:225], v213 offset:28672
	ds_read_b128 v[226:229], v214 offset:28672
	v_exp_f32_e32 v0, v90
	v_exp_f32_e32 v177, v91
	v_exp_f32_e32 v179, v92
	v_exp_f32_e32 v254, v93
	v_add_f32_e32 v219, v0, v219
	v_add_f32_e32 v219, v177, v219
	v_cvt_pk_fp8_f32 v248, v0, v177
	v_add_f32_e32 v219, v179, v219
	v_add_f32_e32 v219, v254, v219
	v_cvt_pk_fp8_f32 v248, v179, v254 op_sel:[0,0,1]
	v_exp_f32_e32 v0, v94
	v_exp_f32_e32 v177, v95
	v_exp_f32_e32 v179, v96
	v_exp_f32_e32 v254, v97
	v_add_f32_e32 v219, v0, v219
	v_add_f32_e32 v219, v177, v219
	v_cvt_pk_fp8_f32 v249, v0, v177
	v_add_f32_e32 v219, v179, v219
	v_add_f32_e32 v219, v254, v219
	v_cvt_pk_fp8_f32 v249, v179, v254 op_sel:[0,0,1]
	ds_read_b128 v[90:93], v185 offset:36864
	ds_read_b128 v[94:97], v186 offset:36864
	s_waitcnt lgkmcnt(4)
	v_mfma_scale_f32_32x32x64_f8f6f4 v[114:129], v[82:89], v[138:145], v[114:129], v194, v193 op_sel_hi:[0,0,0]
	v_exp_f32_e32 v0, v66
	v_exp_f32_e32 v177, v67
	v_exp_f32_e32 v179, v68
	v_exp_f32_e32 v254, v69
	v_add_f32_e32 v219, v0, v219
	v_add_f32_e32 v219, v177, v219
	v_cvt_pk_fp8_f32 v250, v0, v177
	v_add_f32_e32 v219, v179, v219
	v_add_f32_e32 v219, v254, v219
	v_cvt_pk_fp8_f32 v250, v179, v254 op_sel:[0,0,1]
	s_waitcnt lgkmcnt(2)
	v_mfma_scale_f32_32x32x64_f8f6f4 v[98:113], v[222:229], v[138:145], v[98:113], v194, v193 op_sel_hi:[0,0,0]
	ds_read_b128 v[222:225], v185 offset:38912
	ds_read_b128 v[226:229], v186 offset:38912
	v_exp_f32_e32 v0, v70
	v_exp_f32_e32 v177, v71
	v_exp_f32_e32 v179, v72
	v_exp_f32_e32 v254, v73
	v_add_f32_e32 v219, v0, v219
	v_add_f32_e32 v219, v177, v219
	v_cvt_pk_fp8_f32 v251, v0, v177
	v_add_f32_e32 v219, v179, v219
	v_add_f32_e32 v219, v254, v219
	v_cvt_pk_fp8_f32 v251, v179, v254 op_sel:[0,0,1]
	v_exp_f32_e32 v0, v74
	v_exp_f32_e32 v177, v75
	v_exp_f32_e32 v179, v76
	v_exp_f32_e32 v254, v77
	v_add_f32_e32 v219, v0, v219
	v_add_f32_e32 v219, v177, v219
	v_cvt_pk_fp8_f32 v252, v0, v177
	v_add_f32_e32 v219, v179, v219
	v_add_f32_e32 v219, v254, v219
	v_cvt_pk_fp8_f32 v252, v179, v254 op_sel:[0,0,1]
	s_waitcnt lgkmcnt(2)
	v_mfma_scale_f32_32x32x64_f8f6f4 v[114:129], v[90:97], v[130:137], v[114:129], v194, v193 op_sel_hi:[0,0,0]
	v_exp_f32_e32 v0, v78
	v_exp_f32_e32 v177, v79
	v_exp_f32_e32 v179, v80
	v_exp_f32_e32 v254, v81
	v_add_f32_e32 v219, v0, v219
	v_add_f32_e32 v219, v177, v219
	v_cvt_pk_fp8_f32 v253, v0, v177
	v_add_f32_e32 v219, v179, v219
	v_add_f32_e32 v219, v254, v219
	v_cvt_pk_fp8_f32 v253, v179, v254 op_sel:[0,0,1]
	ds_read_b128 v[90:93], v185 offset:0
	ds_read_b128 v[94:97], v186 offset:0
	ds_read_b128 v[82:85], v185 offset:2048
	ds_read_b128 v[86:89], v186 offset:2048
	ds_read_b128 v[74:77], v185 offset:4096
	ds_read_b128 v[78:81], v186 offset:4096
	ds_read_b128 v[66:69], v185 offset:6144
	ds_read_b128 v[70:73], v186 offset:6144
	s_waitcnt lgkmcnt(8)
	v_mfma_scale_f32_32x32x64_f8f6f4 v[98:113], v[222:229], v[130:137], v[98:113], v194, v193 op_sel_hi:[0,0,0]
	v_mov_b32_e32 v0, v219
	s_nop 1
	v_permlane32_swap_b32_e32 v219, v0
	v_add_f32_e32 v219, v219, v0
	v_fma_f32 v209, v209, v218, v219
	v_add_u32_e32 v176, 0x2000, v176
	v_add_u32_e32 v178, 0x20000, v178
	s_mov_b64 s[20:21], 0x1000
	v_lshl_add_u64 v[180:181], v[180:181], 0, s[20:21]
	v_max_f32_e32 v177, v114, v115
	v_max3_f32 v177, v177, v116, v117
	v_max3_f32 v177, v177, v118, v119
	v_max3_f32 v177, v177, v120, v121
	v_max3_f32 v177, v177, v122, v123
	v_max3_f32 v177, v177, v124, v125
	v_max3_f32 v177, v177, v126, v127
	v_max3_f32 v177, v177, v128, v129
	s_waitcnt lgkmcnt(6)
	v_mfma_scale_f32_32x32x64_f8f6f4 v[50:65], v[246:253], v[90:97], v[50:65], v194, v194 op_sel_hi:[0,0,0]
	v_max_f32_e32 v0, v98, v99
	v_max3_f32 v0, v0, v100, v101
	v_max3_f32 v0, v0, v102, v103
	s_waitcnt lgkmcnt(4)
	v_mfma_scale_f32_32x32x64_f8f6f4 v[34:49], v[246:253], v[82:89], v[34:49], v194, v194 op_sel_hi:[0,0,0]
	v_max3_f32 v0, v0, v104, v105
	v_max3_f32 v0, v0, v106, v107
	v_max3_f32 v0, v0, v108, v109
	s_waitcnt lgkmcnt(2)
	v_mfma_scale_f32_32x32x64_f8f6f4 v[18:33], v[246:253], v[74:81], v[18:33], v194, v194 op_sel_hi:[0,0,0]
	v_max3_f32 v0, v0, v110, v111
	v_max3_f32 v0, v0, v112, v113
	v_max_f32_e32 v177, v177, v0
	v_mov_b32_e32 v0, v177
	v_mov_b32_e32 v221, 1.0
	s_waitcnt lgkmcnt(0)
	v_mfma_scale_f32_32x32x64_f8f6f4 v[2:17], v[246:253], v[66:73], v[2:17], v194, v194 op_sel_hi:[0,0,0]
	s_waitcnt vmcnt(0)
	ds_write_b128 v210, v[158:161] offset:43008
	ds_write_b128 v211, v[162:165] offset:51200
	ds_write_b128 v212, v[154:157] offset:59392
	v_permlane32_swap_b32_e32 v177, v0
	v_max_f32_e32 v177, v177, v0
	v_cmp_ge_f32_e32 vcc, s90, v177
	s_cmp_eq_u64 vcc, exec
	s_cbranch_scc0 .Lmla_h0_newmax
; __device__ __forceinline__ void finishSM9(f32x16& p0, f32x16& p1, float alpha, float& l_reg, v8i32& p8) {
; #pragma unroll
;   for (int r = 0; r < 16; ++r) { p0[r] = __builtin_amdgcn_exp2f(p0[r]); p1[r] = __builtin_amdgcn_exp2f(p1[r]); }
;   float ps = 0;
; #pragma unroll
;   for (int r = 0; r < 16; ++r) ps += p0[r];
; #pragma unroll
;   for (int r = 0; r < 16; ++r) ps += p1[r];
;   { auto rr = __builtin_amdgcn_permlane32_swap(__float_as_uint(ps), __float_as_uint(ps), false, false);
;     ps = __uint_as_float(rr[0]) + __uint_as_float(rr[1]); }
;   l_reg = l_reg * alpha + ps;
; #pragma unroll
;   for (int g = 0; g < 4; ++g) {
;     int w = __builtin_amdgcn_cvt_pk_fp8_f32(p0[4 * g], p0[4 * g + 1], 0, false); p8[g] = __builtin_amdgcn_cvt_pk_fp8_f32(p0[4 * g + 2], p0[4 * g + 3], w, true);
;     int u = __builtin_amdgcn_cvt_pk_fp8_f32(p1[4 * g], p1[4 * g + 1], 0, false); p8[4 + g] = __builtin_amdgcn_cvt_pk_fp8_f32(p1[4 * g + 2], p1[4 * g + 3], u, true); }
; }
; __device__ __forceinline__ void pv8(f32x16* o, const char* Vt, const v8i32 p8, int r32, int hi) {
;   const int sw = (r32 >> 2) & 3, a0 = r32 * 64 + (((hi * 2) ^ sw) << 4), a1 = r32 * 64 + (((hi * 2 + 1) ^ sw) << 4);
; #pragma unroll
;   for (int d0 = 0; d0 < 4; ++d0) {
;     const v8i32 vf = cat8(*reinterpret_cast<const v4i32*>(Vt + d0 * 2048 + a0), *reinterpret_cast<const v4i32*>(Vt + d0 * 2048 + a1));
;     o[d0] = __builtin_amdgcn_mfma_scale_f32_32x32x64_f8f6f4(p8, vf, o[d0], 0, 0, 0, 127, 0, 127); }
; }
; __device__ __forceinline__ void qkt9(f32x16& p0, f32x16& p1, const char* Kn, const char* Kr, const v8i32* qf, const float init, int r32, int hi) {
; #pragma unroll
;   for (int r = 0; r < 16; ++r) { p0[r] = init; p1[r] = init; }
; #pragma unroll
;   for (int s = 0; s < 2; ++s) { const int c0 = s * 4 + hi * 2;
;     const v8i32 a0 = cat8(*reinterpret_cast<const v4i32*>(Kn + KN8SW(r32, c0)), *reinterpret_cast<const v4i32*>(Kn + KN8SW(r32, c0 + 1)));
;     const v8i32 a1 = cat8(*reinterpret_cast<const v4i32*>(Kn + 4096 + KN8SW(r32, c0)), *reinterpret_cast<const v4i32*>(Kn + 4096 + KN8SW(r32, c0 + 1)));
;     p0 = __builtin_amdgcn_mfma_scale_f32_32x32x64_f8f6f4(a0, qf[s], p0, 0, 0, 0, 127, 0, 124);
;     p1 = __builtin_amdgcn_mfma_scale_f32_32x32x64_f8f6f4(a1, qf[s], p1, 0, 0, 0, 127, 0, 124); }
;   { const int c0 = hi * 2;
.Lmla_h0_cont:
	s_waitcnt lgkmcnt(0)
	s_barrier
	global_load_dwordx4 v[158:161], v176, s[18:19]
	global_load_dwordx4 v[162:165], v178, s[16:17]
	global_load_dwordx4 v[154:157], v[180:181], off
	ds_read_b128 v[82:85], v215 offset:51200
	ds_read_b128 v[86:89], v216 offset:51200
	ds_read_b128 v[222:225], v215 offset:55296
	ds_read_b128 v[226:229], v216 offset:55296
	v_exp_f32_e32 v0, v114
	v_exp_f32_e32 v177, v115
	v_exp_f32_e32 v179, v116
	v_exp_f32_e32 v254, v117
	v_add_f32_e32 v219, v0, v177
	v_cvt_pk_fp8_f32 v246, v0, v177
	v_add_f32_e32 v219, v179, v219
	v_add_f32_e32 v219, v254, v219
	v_cvt_pk_fp8_f32 v246, v179, v254 op_sel:[0,0,1]
	s_waitcnt lgkmcnt(2)
	v_mfma_scale_f32_32x32x64_f8f6f4 v[82:97], v[82:89], v[146:153], v[230:245], v194, v193 op_sel_hi:[0,0,0]
	v_exp_f32_e32 v0, v118
	v_exp_f32_e32 v177, v119
	v_exp_f32_e32 v179, v120
	v_exp_f32_e32 v254, v121
	v_add_f32_e32 v219, v0, v219
	v_add_f32_e32 v219, v177, v219
	v_cvt_pk_fp8_f32 v247, v0, v177
	v_add_f32_e32 v219, v179, v219
	v_add_f32_e32 v219, v254, v219
	v_cvt_pk_fp8_f32 v247, v179, v254 op_sel:[0,0,1]
	ds_read_b128 v[114:117], v213 offset:51200
	ds_read_b128 v[118:121], v214 offset:51200
	s_waitcnt lgkmcnt(2)
	v_mfma_scale_f32_32x32x64_f8f6f4 v[66:81], v[222:229], v[146:153], v[230:245], v194, v193 op_sel_hi:[0,0,0]
	ds_read_b128 v[222:225], v213 offset:55296
	ds_read_b128 v[226:229], v214 offset:55296
	v_exp_f32_e32 v0, v122
	v_exp_f32_e32 v177, v123
	v_exp_f32_e32 v179, v124
	v_exp_f32_e32 v254, v125
	v_add_f32_e32 v219, v0, v219
	v_add_f32_e32 v219, v177, v219
	v_cvt_pk_fp8_f32 v248, v0, v177
	v_add_f32_e32 v219, v179, v219
	v_add_f32_e32 v219, v254, v219
	v_cvt_pk_fp8_f32 v248, v179, v254 op_sel:[0,0,1]
	v_exp_f32_e32 v0, v126
	v_exp_f32_e32 v177, v127
	v_exp_f32_e32 v179, v128
	v_exp_f32_e32 v254, v129
	v_add_f32_e32 v219, v0, v219
	v_add_f32_e32 v219, v177, v219
	v_cvt_pk_fp8_f32 v249, v0, v177
	v_add_f32_e32 v219, v179, v219
	v_add_f32_e32 v219, v254, v219
	v_cvt_pk_fp8_f32 v249, v179, v254 op_sel:[0,0,1]
	ds_read_b128 v[122:125], v185 offset:59392
	ds_read_b128 v[126:129], v186 offset:59392
	s_waitcnt lgkmcnt(4)
	v_mfma_scale_f32_32x32x64_f8f6f4 v[82:97], v[114:121], v[138:145], v[82:97], v194, v193 op_sel_hi:[0,0,0]
	v_exp_f32_e32 v0, v98
	v_exp_f32_e32 v177, v99
	v_exp_f32_e32 v179, v100
	v_exp_f32_e32 v254, v101
	v_add_f32_e32 v219, v0, v219
	v_add_f32_e32 v219, v177, v219
	v_cvt_pk_fp8_f32 v250, v0, v177
	v_add_f32_e32 v219, v179, v219
	v_add_f32_e32 v219, v254, v219
	v_cvt_pk_fp8_f32 v250, v179, v254 op_sel:[0,0,1]
	s_waitcnt lgkmcnt(2)
	v_mfma_scale_f32_32x32x64_f8f6f4 v[66:81], v[222:229], v[138:145], v[66:81], v194, v193 op_sel_hi:[0,0,0]
	ds_read_b128 v[222:225], v185 offset:61440
	ds_read_b128 v[226:229], v186 offset:61440
	v_exp_f32_e32 v0, v102
	v_exp_f32_e32 v177, v103
	v_exp_f32_e32 v179, v104
	v_exp_f32_e32 v254, v105
	v_add_f32_e32 v219, v0, v219
	v_add_f32_e32 v219, v177, v219
	v_cvt_pk_fp8_f32 v251, v0, v177
	v_add_f32_e32 v219, v179, v219
	v_add_f32_e32 v219, v254, v219
	v_cvt_pk_fp8_f32 v251, v179, v254 op_sel:[0,0,1]
	v_exp_f32_e32 v0, v106
	v_exp_f32_e32 v177, v107
	v_exp_f32_e32 v179, v108
	v_exp_f32_e32 v254, v109
	v_add_f32_e32 v219, v0, v219
	v_add_f32_e32 v219, v177, v219
	v_cvt_pk_fp8_f32 v252, v0, v177
	v_add_f32_e32 v219, v179, v219
	v_add_f32_e32 v219, v254, v219
	v_cvt_pk_fp8_f32 v252, v179, v254 op_sel:[0,0,1]
	s_waitcnt lgkmcnt(2)
	v_mfma_scale_f32_32x32x64_f8f6f4 v[82:97], v[122:129], v[130:137], v[82:97], v194, v193 op_sel_hi:[0,0,0]
	v_exp_f32_e32 v0, v110
	v_exp_f32_e32 v177, v111
	v_exp_f32_e32 v179, v112
	v_exp_f32_e32 v254, v113
	v_add_f32_e32 v219, v0, v219
	v_add_f32_e32 v219, v177, v219
	v_cvt_pk_fp8_f32 v253, v0, v177
	v_add_f32_e32 v219, v179, v219
	v_add_f32_e32 v219, v254, v219
	v_cvt_pk_fp8_f32 v253, v179, v254 op_sel:[0,0,1]
	ds_read_b128 v[122:125], v185 offset:8192
	ds_read_b128 v[126:129], v186 offset:8192
	ds_read_b128 v[114:117], v185 offset:10240
	ds_read_b128 v[118:121], v186 offset:10240
	ds_read_b128 v[106:109], v185 offset:12288
	ds_read_b128 v[110:113], v186 offset:12288
	ds_read_b128 v[98:101], v185 offset:14336
	ds_read_b128 v[102:105], v186 offset:14336
	s_waitcnt lgkmcnt(8)
	v_mfma_scale_f32_32x32x64_f8f6f4 v[66:81], v[222:229], v[130:137], v[66:81], v194, v193 op_sel_hi:[0,0,0]
	v_mov_b32_e32 v0, v219
	s_nop 1
	v_permlane32_swap_b32_e32 v219, v0
	v_add_f32_e32 v219, v219, v0
	v_fma_f32 v209, v209, v221, v219
	v_add_u32_e32 v176, 0x2000, v176
	v_add_u32_e32 v178, 0x20000, v178
	s_mov_b64 s[20:21], 0x1000
	v_lshl_add_u64 v[180:181], v[180:181], 0, s[20:21]
	v_max_f32_e32 v177, v82, v83
	v_max3_f32 v177, v177, v84, v85
	v_max3_f32 v177, v177, v86, v87
	v_max3_f32 v177, v177, v88, v89
	v_max3_f32 v177, v177, v90, v91
	v_max3_f32 v177, v177, v92, v93
	v_max3_f32 v177, v177, v94, v95
	v_max3_f32 v177, v177, v96, v97
	s_waitcnt lgkmcnt(6)
	v_mfma_scale_f32_32x32x64_f8f6f4 v[50:65], v[246:253], v[122:129], v[50:65], v194, v194 op_sel_hi:[0,0,0]
	v_max_f32_e32 v0, v66, v67
	v_max3_f32 v0, v0, v68, v69
	v_max3_f32 v0, v0, v70, v71
	s_waitcnt lgkmcnt(4)
	v_mfma_scale_f32_32x32x64_f8f6f4 v[34:49], v[246:253], v[114:121], v[34:49], v194, v194 op_sel_hi:[0,0,0]
	v_max3_f32 v0, v0, v72, v73
	v_max3_f32 v0, v0, v74, v75
	v_max3_f32 v0, v0, v76, v77
	s_waitcnt lgkmcnt(2)
	v_mfma_scale_f32_32x32x64_f8f6f4 v[18:33], v[246:253], v[106:113], v[18:33], v194, v194 op_sel_hi:[0,0,0]
	v_max3_f32 v0, v0, v78, v79
	v_max3_f32 v0, v0, v80, v81
	v_max_f32_e32 v177, v177, v0
	v_mov_b32_e32 v0, v177
	v_mov_b32_e32 v218, 1.0
	s_waitcnt lgkmcnt(0)
	v_mfma_scale_f32_32x32x64_f8f6f4 v[2:17], v[246:253], v[98:105], v[2:17], v194, v194 op_sel_hi:[0,0,0]
	s_waitcnt vmcnt(0)
	ds_write_b128 v210, v[158:161]
	ds_write_b128 v211, v[162:165] offset:16384
	ds_write_b128 v212, v[154:157] offset:32768
	v_permlane32_swap_b32_e32 v177, v0
	v_max_f32_e32 v177, v177, v0
	v_cmp_ge_f32_e32 vcc, s90, v177
	s_cmp_eq_u64 vcc, exec
	s_cbranch_scc0 .Lmla_h1_newmax
; __device__ __forceinline__ void finishSM9(f32x16& p0, f32x16& p1, float alpha, float& l_reg, v8i32& p8) {
; #pragma unroll
;   for (int r = 0; r < 16; ++r) { p0[r] = __builtin_amdgcn_exp2f(p0[r]); p1[r] = __builtin_amdgcn_exp2f(p1[r]); }
;   float ps = 0;
; #pragma unroll
;   for (int r = 0; r < 16; ++r) ps += p0[r];
; #pragma unroll
;   for (int r = 0; r < 16; ++r) ps += p1[r];
;   { auto rr = __builtin_amdgcn_permlane32_swap(__float_as_uint(ps), __float_as_uint(ps), false, false);
;     ps = __uint_as_float(rr[0]) + __uint_as_float(rr[1]); }
;   l_reg = l_reg * alpha + ps;
; #pragma unroll
;   for (int g = 0; g < 4; ++g) {
;     int w = __builtin_amdgcn_cvt_pk_fp8_f32(p0[4 * g], p0[4 * g + 1], 0, false); p8[g] = __builtin_amdgcn_cvt_pk_fp8_f32(p0[4 * g + 2], p0[4 * g + 3], w, true);
;     int u = __builtin_amdgcn_cvt_pk_fp8_f32(p1[4 * g], p1[4 * g + 1], 0, false); p8[4 + g] = __builtin_amdgcn_cvt_pk_fp8_f32(p1[4 * g + 2], p1[4 * g + 3], u, true); }
; }
; __device__ __forceinline__ void pv8(f32x16* o, const char* Vt, const v8i32 p8, int r32, int hi) {
;   const int sw = (r32 >> 2) & 3, a0 = r32 * 64 + (((hi * 2) ^ sw) << 4), a1 = r32 * 64 + (((hi * 2 + 1) ^ sw) << 4);
; #pragma unroll
;   for (int d0 = 0; d0 < 4; ++d0) {
;     const v8i32 vf = cat8(*reinterpret_cast<const v4i32*>(Vt + d0 * 2048 + a0), *reinterpret_cast<const v4i32*>(Vt + d0 * 2048 + a1));
;     o[d0] = __builtin_amdgcn_mfma_scale_f32_32x32x64_f8f6f4(p8, vf, o[d0], 0, 0, 0, 127, 0, 127); }
; }
; __device__ __forceinline__ void qkt9(f32x16& p0, f32x16& p1, const char* Kn, const char* Kr, const v8i32* qf, const float init, int r32, int hi) {
; #pragma unroll
;   for (int r = 0; r < 16; ++r) { p0[r] = init; p1[r] = init; }
; #pragma unroll
;   for (int s = 0; s < 2; ++s) { const int c0 = s * 4 + hi * 2;
;     const v8i32 a0 = cat8(*reinterpret_cast<const v4i32*>(Kn + KN8SW(r32, c0)), *reinterpret_cast<const v4i32*>(Kn + KN8SW(r32, c0 + 1)));
;     const v8i32 a1 = cat8(*reinterpret_cast<const v4i32*>(Kn + 4096 + KN8SW(r32, c0)), *reinterpret_cast<const v4i32*>(Kn + 4096 + KN8SW(r32, c0 + 1)));
;     p0 = __builtin_amdgcn_mfma_scale_f32_32x32x64_f8f6f4(a0, qf[s], p0, 0, 0, 0, 127, 0, 124);
;     p1 = __builtin_amdgcn_mfma_scale_f32_32x32x64_f8f6f4(a1, qf[s], p1, 0, 0, 0, 127, 0, 124); }
;   { const int c0 = hi * 2;
.Lmla_h1_cont:
	s_waitcnt lgkmcnt(0)
	s_barrier
	global_load_dwordx4 v[158:161], v176, s[18:19]
	global_load_dwordx4 v[162:165], v178, s[16:17]
	global_load_dwordx4 v[154:157], v[180:181], off
	ds_read_b128 v[114:117], v215 offset:16384
	ds_read_b128 v[118:121], v216 offset:16384
	ds_read_b128 v[222:225], v215 offset:20480
	ds_read_b128 v[226:229], v216 offset:20480
	v_exp_f32_e32 v0, v82
	v_exp_f32_e32 v177, v83
	v_exp_f32_e32 v179, v84
	v_exp_f32_e32 v254, v85
	v_add_f32_e32 v219, v0, v177
	v_cvt_pk_fp8_f32 v246, v0, v177
	v_add_f32_e32 v219, v179, v219
	v_add_f32_e32 v219, v254, v219
	v_cvt_pk_fp8_f32 v246, v179, v254 op_sel:[0,0,1]
	s_waitcnt lgkmcnt(2)
	v_mfma_scale_f32_32x32x64_f8f6f4 v[114:129], v[114:121], v[146:153], v[230:245], v194, v193 op_sel_hi:[0,0,0]
	v_exp_f32_e32 v0, v86
	v_exp_f32_e32 v177, v87
	v_exp_f32_e32 v179, v88
	v_exp_f32_e32 v254, v89
	v_add_f32_e32 v219, v0, v219
	v_add_f32_e32 v219, v177, v219
	v_cvt_pk_fp8_f32 v247, v0, v177
	v_add_f32_e32 v219, v179, v219
	v_add_f32_e32 v219, v254, v219
	v_cvt_pk_fp8_f32 v247, v179, v254 op_sel:[0,0,1]
	ds_read_b128 v[82:85], v213 offset:16384
	ds_read_b128 v[86:89], v214 offset:16384
	s_waitcnt lgkmcnt(2)
	v_mfma_scale_f32_32x32x64_f8f6f4 v[98:113], v[222:229], v[146:153], v[230:245], v194, v193 op_sel_hi:[0,0,0]
	ds_read_b128 v[222:225], v213 offset:20480
	ds_read_b128 v[226:229], v214 offset:20480
	v_exp_f32_e32 v0, v90
	v_exp_f32_e32 v177, v91
	v_exp_f32_e32 v179, v92
	v_exp_f32_e32 v254, v93
	v_add_f32_e32 v219, v0, v219
	v_add_f32_e32 v219, v177, v219
	v_cvt_pk_fp8_f32 v248, v0, v177
	v_add_f32_e32 v219, v179, v219
	v_add_f32_e32 v219, v254, v219
	v_cvt_pk_fp8_f32 v248, v179, v254 op_sel:[0,0,1]
	v_exp_f32_e32 v0, v94
	v_exp_f32_e32 v177, v95
	v_exp_f32_e32 v179, v96
	v_exp_f32_e32 v254, v97
	v_add_f32_e32 v219, v0, v219
	v_add_f32_e32 v219, v177, v219
	v_cvt_pk_fp8_f32 v249, v0, v177
	v_add_f32_e32 v219, v179, v219
	v_add_f32_e32 v219, v254, v219
	v_cvt_pk_fp8_f32 v249, v179, v254 op_sel:[0,0,1]
	ds_read_b128 v[90:93], v185 offset:32768
	ds_read_b128 v[94:97], v186 offset:32768
	s_waitcnt lgkmcnt(4)
	v_mfma_scale_f32_32x32x64_f8f6f4 v[114:129], v[82:89], v[138:145], v[114:129], v194, v193 op_sel_hi:[0,0,0]
	v_exp_f32_e32 v0, v66
	v_exp_f32_e32 v177, v67
	v_exp_f32_e32 v179, v68
	v_exp_f32_e32 v254, v69
	v_add_f32_e32 v219, v0, v219
	v_add_f32_e32 v219, v177, v219
	v_cvt_pk_fp8_f32 v250, v0, v177
	v_add_f32_e32 v219, v179, v219
	v_add_f32_e32 v219, v254, v219
	v_cvt_pk_fp8_f32 v250, v179, v254 op_sel:[0,0,1]
	s_waitcnt lgkmcnt(2)
	v_mfma_scale_f32_32x32x64_f8f6f4 v[98:113], v[222:229], v[138:145], v[98:113], v194, v193 op_sel_hi:[0,0,0]
	ds_read_b128 v[222:225], v185 offset:34816
	ds_read_b128 v[226:229], v186 offset:34816
	v_exp_f32_e32 v0, v70
	v_exp_f32_e32 v177, v71
	v_exp_f32_e32 v179, v72
	v_exp_f32_e32 v254, v73
	v_add_f32_e32 v219, v0, v219
	v_add_f32_e32 v219, v177, v219
	v_cvt_pk_fp8_f32 v251, v0, v177
	v_add_f32_e32 v219, v179, v219
	v_add_f32_e32 v219, v254, v219
	v_cvt_pk_fp8_f32 v251, v179, v254 op_sel:[0,0,1]
	v_exp_f32_e32 v0, v74
	v_exp_f32_e32 v177, v75
	v_exp_f32_e32 v179, v76
	v_exp_f32_e32 v254, v77
	v_add_f32_e32 v219, v0, v219
	v_add_f32_e32 v219, v177, v219
	v_cvt_pk_fp8_f32 v252, v0, v177
	v_add_f32_e32 v219, v179, v219
	v_add_f32_e32 v219, v254, v219
	v_cvt_pk_fp8_f32 v252, v179, v254 op_sel:[0,0,1]
	s_waitcnt lgkmcnt(2)
	v_mfma_scale_f32_32x32x64_f8f6f4 v[114:129], v[90:97], v[130:137], v[114:129], v194, v193 op_sel_hi:[0,0,0]
	v_exp_f32_e32 v0, v78
	v_exp_f32_e32 v177, v79
	v_exp_f32_e32 v179, v80
	v_exp_f32_e32 v254, v81
	v_add_f32_e32 v219, v0, v219
	v_add_f32_e32 v219, v177, v219
	v_cvt_pk_fp8_f32 v253, v0, v177
	v_add_f32_e32 v219, v179, v219
	v_add_f32_e32 v219, v254, v219
	v_cvt_pk_fp8_f32 v253, v179, v254 op_sel:[0,0,1]
	ds_read_b128 v[90:93], v185 offset:43008
	ds_read_b128 v[94:97], v186 offset:43008
	ds_read_b128 v[82:85], v185 offset:45056
	ds_read_b128 v[86:89], v186 offset:45056
	ds_read_b128 v[74:77], v185 offset:47104
	ds_read_b128 v[78:81], v186 offset:47104
	ds_read_b128 v[66:69], v185 offset:49152
	ds_read_b128 v[70:73], v186 offset:49152
	s_waitcnt lgkmcnt(8)
	v_mfma_scale_f32_32x32x64_f8f6f4 v[98:113], v[222:229], v[130:137], v[98:113], v194, v193 op_sel_hi:[0,0,0]
	v_mov_b32_e32 v0, v219
	s_nop 1
	v_permlane32_swap_b32_e32 v219, v0
	v_add_f32_e32 v219, v219, v0
	v_fma_f32 v209, v209, v218, v219
	v_add_u32_e32 v176, 0x2000, v176
	v_add_u32_e32 v178, 0x20000, v178
	s_mov_b64 s[20:21], 0x1000
	v_lshl_add_u64 v[180:181], v[180:181], 0, s[20:21]
	v_max_f32_e32 v177, v114, v115
	v_max3_f32 v177, v177, v116, v117
	v_max3_f32 v177, v177, v118, v119
	v_max3_f32 v177, v177, v120, v121
	v_max3_f32 v177, v177, v122, v123
	v_max3_f32 v177, v177, v124, v125
	v_max3_f32 v177, v177, v126, v127
	v_max3_f32 v177, v177, v128, v129
	s_waitcnt lgkmcnt(6)
	v_mfma_scale_f32_32x32x64_f8f6f4 v[50:65], v[246:253], v[90:97], v[50:65], v194, v194 op_sel_hi:[0,0,0]
	v_max_f32_e32 v0, v98, v99
	v_max3_f32 v0, v0, v100, v101
	v_max3_f32 v0, v0, v102, v103
	s_waitcnt lgkmcnt(4)
	v_mfma_scale_f32_32x32x64_f8f6f4 v[34:49], v[246:253], v[82:89], v[34:49], v194, v194 op_sel_hi:[0,0,0]
	v_max3_f32 v0, v0, v104, v105
	v_max3_f32 v0, v0, v106, v107
	v_max3_f32 v0, v0, v108, v109
	s_waitcnt lgkmcnt(2)
	v_mfma_scale_f32_32x32x64_f8f6f4 v[18:33], v[246:253], v[74:81], v[18:33], v194, v194 op_sel_hi:[0,0,0]
	v_max3_f32 v0, v0, v110, v111
	v_max3_f32 v0, v0, v112, v113
	v_max_f32_e32 v177, v177, v0
	v_mov_b32_e32 v0, v177
	v_mov_b32_e32 v221, 1.0
	s_waitcnt lgkmcnt(0)
	v_mfma_scale_f32_32x32x64_f8f6f4 v[2:17], v[246:253], v[66:73], v[2:17], v194, v194 op_sel_hi:[0,0,0]
	s_waitcnt vmcnt(0)
	ds_write_b128 v210, v[158:161] offset:8192
	ds_write_b128 v211, v[162:165] offset:24576
	ds_write_b128 v212, v[154:157] offset:36864
	v_permlane32_swap_b32_e32 v177, v0
	v_max_f32_e32 v177, v177, v0
	v_cmp_ge_f32_e32 vcc, s90, v177
	s_cmp_eq_u64 vcc, exec
	s_cbranch_scc0 .Lmla_h2_newmax
; __device__ __forceinline__ void finishSM9(f32x16& p0, f32x16& p1, float alpha, float& l_reg, v8i32& p8) {
; #pragma unroll
;   for (int r = 0; r < 16; ++r) { p0[r] = __builtin_amdgcn_exp2f(p0[r]); p1[r] = __builtin_amdgcn_exp2f(p1[r]); }
;   float ps = 0;
; #pragma unroll
;   for (int r = 0; r < 16; ++r) ps += p0[r];
; #pragma unroll
;   for (int r = 0; r < 16; ++r) ps += p1[r];
;   { auto rr = __builtin_amdgcn_permlane32_swap(__float_as_uint(ps), __float_as_uint(ps), false, false);
;     ps = __uint_as_float(rr[0]) + __uint_as_float(rr[1]); }
;   l_reg = l_reg * alpha + ps;
; #pragma unroll
;   for (int g = 0; g < 4; ++g) {
;     int w = __builtin_amdgcn_cvt_pk_fp8_f32(p0[4 * g], p0[4 * g + 1], 0, false); p8[g] = __builtin_amdgcn_cvt_pk_fp8_f32(p0[4 * g + 2], p0[4 * g + 3], w, true);
;     int u = __builtin_amdgcn_cvt_pk_fp8_f32(p1[4 * g], p1[4 * g + 1], 0, false); p8[4 + g] = __builtin_amdgcn_cvt_pk_fp8_f32(p1[4 * g + 2], p1[4 * g + 3], u, true); }
; }
; __device__ __forceinline__ void pv8(f32x16* o, const char* Vt, const v8i32 p8, int r32, int hi) {
;   const int sw = (r32 >> 2) & 3, a0 = r32 * 64 + (((hi * 2) ^ sw) << 4), a1 = r32 * 64 + (((hi * 2 + 1) ^ sw) << 4);
; #pragma unroll
;   for (int d0 = 0; d0 < 4; ++d0) {
;     const v8i32 vf = cat8(*reinterpret_cast<const v4i32*>(Vt + d0 * 2048 + a0), *reinterpret_cast<const v4i32*>(Vt + d0 * 2048 + a1));
;     o[d0] = __builtin_amdgcn_mfma_scale_f32_32x32x64_f8f6f4(p8, vf, o[d0], 0, 0, 0, 127, 0, 127); }
; }
; __device__ __forceinline__ void qkt9(f32x16& p0, f32x16& p1, const char* Kn, const char* Kr, const v8i32* qf, const float init, int r32, int hi) {
; #pragma unroll
;   for (int r = 0; r < 16; ++r) { p0[r] = init; p1[r] = init; }
; #pragma unroll
;   for (int s = 0; s < 2; ++s) { const int c0 = s * 4 + hi * 2;
;     const v8i32 a0 = cat8(*reinterpret_cast<const v4i32*>(Kn + KN8SW(r32, c0)), *reinterpret_cast<const v4i32*>(Kn + KN8SW(r32, c0 + 1)));
;     const v8i32 a1 = cat8(*reinterpret_cast<const v4i32*>(Kn + 4096 + KN8SW(r32, c0)), *reinterpret_cast<const v4i32*>(Kn + 4096 + KN8SW(r32, c0 + 1)));
;     p0 = __builtin_amdgcn_mfma_scale_f32_32x32x64_f8f6f4(a0, qf[s], p0, 0, 0, 0, 127, 0, 124);
;     p1 = __builtin_amdgcn_mfma_scale_f32_32x32x64_f8f6f4(a1, qf[s], p1, 0, 0, 0, 127, 0, 124); }
;   { const int c0 = hi * 2;
.Lmla_h2_cont:
	s_waitcnt lgkmcnt(0)
	s_barrier
	global_load_dwordx4 v[158:161], v176, s[18:19]
	global_load_dwordx4 v[162:165], v178, s[16:17]
	global_load_dwordx4 v[154:157], v[180:181], off
	ds_read_b128 v[82:85], v215 offset:24576
	ds_read_b128 v[86:89], v216 offset:24576
	ds_read_b128 v[222:225], v215 offset:28672
	ds_read_b128 v[226:229], v216 offset:28672
	v_exp_f32_e32 v0, v114
	v_exp_f32_e32 v177, v115
	v_exp_f32_e32 v179, v116
	v_exp_f32_e32 v254, v117
	v_add_f32_e32 v219, v0, v177
	v_cvt_pk_fp8_f32 v246, v0, v177
	v_add_f32_e32 v219, v179, v219
	v_add_f32_e32 v219, v254, v219
	v_cvt_pk_fp8_f32 v246, v179, v254 op_sel:[0,0,1]
	s_waitcnt lgkmcnt(2)
	v_mfma_scale_f32_32x32x64_f8f6f4 v[82:97], v[82:89], v[146:153], v[230:245], v194, v193 op_sel_hi:[0,0,0]
	v_exp_f32_e32 v0, v118
	v_exp_f32_e32 v177, v119
	v_exp_f32_e32 v179, v120
	v_exp_f32_e32 v254, v121
	v_add_f32_e32 v219, v0, v219
	v_add_f32_e32 v219, v177, v219
	v_cvt_pk_fp8_f32 v247, v0, v177
	v_add_f32_e32 v219, v179, v219
	v_add_f32_e32 v219, v254, v219
	v_cvt_pk_fp8_f32 v247, v179, v254 op_sel:[0,0,1]
	ds_read_b128 v[114:117], v213 offset:24576
	ds_read_b128 v[118:121], v214 offset:24576
	s_waitcnt lgkmcnt(2)
	v_mfma_scale_f32_32x32x64_f8f6f4 v[66:81], v[222:229], v[146:153], v[230:245], v194, v193 op_sel_hi:[0,0,0]
	ds_read_b128 v[222:225], v213 offset:28672
	ds_read_b128 v[226:229], v214 offset:28672
	v_exp_f32_e32 v0, v122
	v_exp_f32_e32 v177, v123
	v_exp_f32_e32 v179, v124
	v_exp_f32_e32 v254, v125
	v_add_f32_e32 v219, v0, v219
	v_add_f32_e32 v219, v177, v219
	v_cvt_pk_fp8_f32 v248, v0, v177
	v_add_f32_e32 v219, v179, v219
	v_add_f32_e32 v219, v254, v219
	v_cvt_pk_fp8_f32 v248, v179, v254 op_sel:[0,0,1]
	v_exp_f32_e32 v0, v126
	v_exp_f32_e32 v177, v127
	v_exp_f32_e32 v179, v128
	v_exp_f32_e32 v254, v129
	v_add_f32_e32 v219, v0, v219
	v_add_f32_e32 v219, v177, v219
	v_cvt_pk_fp8_f32 v249, v0, v177
	v_add_f32_e32 v219, v179, v219
	v_add_f32_e32 v219, v254, v219
	v_cvt_pk_fp8_f32 v249, v179, v254 op_sel:[0,0,1]
	ds_read_b128 v[122:125], v185 offset:36864
	ds_read_b128 v[126:129], v186 offset:36864
	s_waitcnt lgkmcnt(4)
	v_mfma_scale_f32_32x32x64_f8f6f4 v[82:97], v[114:121], v[138:145], v[82:97], v194, v193 op_sel_hi:[0,0,0]
	v_exp_f32_e32 v0, v98
	v_exp_f32_e32 v177, v99
	v_exp_f32_e32 v179, v100
	v_exp_f32_e32 v254, v101
	v_add_f32_e32 v219, v0, v219
	v_add_f32_e32 v219, v177, v219
	v_cvt_pk_fp8_f32 v250, v0, v177
	v_add_f32_e32 v219, v179, v219
	v_add_f32_e32 v219, v254, v219
	v_cvt_pk_fp8_f32 v250, v179, v254 op_sel:[0,0,1]
	s_waitcnt lgkmcnt(2)
	v_mfma_scale_f32_32x32x64_f8f6f4 v[66:81], v[222:229], v[138:145], v[66:81], v194, v193 op_sel_hi:[0,0,0]
	ds_read_b128 v[222:225], v185 offset:38912
	ds_read_b128 v[226:229], v186 offset:38912
	v_exp_f32_e32 v0, v102
	v_exp_f32_e32 v177, v103
	v_exp_f32_e32 v179, v104
	v_exp_f32_e32 v254, v105
	v_add_f32_e32 v219, v0, v219
	v_add_f32_e32 v219, v177, v219
	v_cvt_pk_fp8_f32 v251, v0, v177
	v_add_f32_e32 v219, v179, v219
	v_add_f32_e32 v219, v254, v219
	v_cvt_pk_fp8_f32 v251, v179, v254 op_sel:[0,0,1]
	v_exp_f32_e32 v0, v106
	v_exp_f32_e32 v177, v107
	v_exp_f32_e32 v179, v108
	v_exp_f32_e32 v254, v109
	v_add_f32_e32 v219, v0, v219
	v_add_f32_e32 v219, v177, v219
	v_cvt_pk_fp8_f32 v252, v0, v177
	v_add_f32_e32 v219, v179, v219
	v_add_f32_e32 v219, v254, v219
	v_cvt_pk_fp8_f32 v252, v179, v254 op_sel:[0,0,1]
	s_waitcnt lgkmcnt(2)
	v_mfma_scale_f32_32x32x64_f8f6f4 v[82:97], v[122:129], v[130:137], v[82:97], v194, v193 op_sel_hi:[0,0,0]
	v_exp_f32_e32 v0, v110
	v_exp_f32_e32 v177, v111
	v_exp_f32_e32 v179, v112
	v_exp_f32_e32 v254, v113
	v_add_f32_e32 v219, v0, v219
	v_add_f32_e32 v219, v177, v219
	v_cvt_pk_fp8_f32 v253, v0, v177
	v_add_f32_e32 v219, v179, v219
	v_add_f32_e32 v219, v254, v219
	v_cvt_pk_fp8_f32 v253, v179, v254 op_sel:[0,0,1]
	ds_read_b128 v[122:125], v185 offset:0
	ds_read_b128 v[126:129], v186 offset:0
	ds_read_b128 v[114:117], v185 offset:2048
	ds_read_b128 v[118:121], v186 offset:2048
	ds_read_b128 v[106:109], v185 offset:4096
	ds_read_b128 v[110:113], v186 offset:4096
	ds_read_b128 v[98:101], v185 offset:6144
	ds_read_b128 v[102:105], v186 offset:6144
	s_waitcnt lgkmcnt(8)
	v_mfma_scale_f32_32x32x64_f8f6f4 v[66:81], v[222:229], v[130:137], v[66:81], v194, v193 op_sel_hi:[0,0,0]
	v_mov_b32_e32 v0, v219
	s_nop 1
	v_permlane32_swap_b32_e32 v219, v0
	v_add_f32_e32 v219, v219, v0
	v_fma_f32 v209, v209, v221, v219
	v_add_u32_e32 v176, 0x2000, v176
	v_add_u32_e32 v178, 0x20000, v178
	s_mov_b64 s[20:21], 0x1000
	v_lshl_add_u64 v[180:181], v[180:181], 0, s[20:21]
	v_max_f32_e32 v177, v82, v83
	v_max3_f32 v177, v177, v84, v85
	v_max3_f32 v177, v177, v86, v87
	v_max3_f32 v177, v177, v88, v89
	v_max3_f32 v177, v177, v90, v91
	v_max3_f32 v177, v177, v92, v93
	v_max3_f32 v177, v177, v94, v95
	v_max3_f32 v177, v177, v96, v97
	s_waitcnt lgkmcnt(6)
	v_mfma_scale_f32_32x32x64_f8f6f4 v[50:65], v[246:253], v[122:129], v[50:65], v194, v194 op_sel_hi:[0,0,0]
	v_max_f32_e32 v0, v66, v67
	v_max3_f32 v0, v0, v68, v69
	v_max3_f32 v0, v0, v70, v71
	s_waitcnt lgkmcnt(4)
	v_mfma_scale_f32_32x32x64_f8f6f4 v[34:49], v[246:253], v[114:121], v[34:49], v194, v194 op_sel_hi:[0,0,0]
	v_max3_f32 v0, v0, v72, v73
	v_max3_f32 v0, v0, v74, v75
	v_max3_f32 v0, v0, v76, v77
	s_waitcnt lgkmcnt(2)
	v_mfma_scale_f32_32x32x64_f8f6f4 v[18:33], v[246:253], v[106:113], v[18:33], v194, v194 op_sel_hi:[0,0,0]
	v_max3_f32 v0, v0, v78, v79
	v_max3_f32 v0, v0, v80, v81
	v_max_f32_e32 v177, v177, v0
	v_mov_b32_e32 v0, v177
	v_mov_b32_e32 v218, 1.0
	s_waitcnt lgkmcnt(0)
	v_mfma_scale_f32_32x32x64_f8f6f4 v[2:17], v[246:253], v[98:105], v[2:17], v194, v194 op_sel_hi:[0,0,0]
	s_waitcnt vmcnt(0)
	ds_write_b128 v210, v[158:161] offset:43008
	ds_write_b128 v211, v[162:165] offset:51200
	ds_write_b128 v212, v[154:157] offset:59392
	v_permlane32_swap_b32_e32 v177, v0
	v_max_f32_e32 v177, v177, v0
	v_cmp_ge_f32_e32 vcc, s90, v177
	s_cmp_eq_u64 vcc, exec
	s_cbranch_scc0 .Lmla_h3_newmax
; __device__ __forceinline__ void finishSM9(f32x16& p0, f32x16& p1, float alpha, float& l_reg, v8i32& p8) {
; #pragma unroll
;   for (int r = 0; r < 16; ++r) { p0[r] = __builtin_amdgcn_exp2f(p0[r]); p1[r] = __builtin_amdgcn_exp2f(p1[r]); }
;   float ps = 0;
; #pragma unroll
;   for (int r = 0; r < 16; ++r) ps += p0[r];
; #pragma unroll
;   for (int r = 0; r < 16; ++r) ps += p1[r];
;   { auto rr = __builtin_amdgcn_permlane32_swap(__float_as_uint(ps), __float_as_uint(ps), false, false);
;     ps = __uint_as_float(rr[0]) + __uint_as_float(rr[1]); }
;   l_reg = l_reg * alpha + ps;
; #pragma unroll
;   for (int g = 0; g < 4; ++g) {
;     int w = __builtin_amdgcn_cvt_pk_fp8_f32(p0[4 * g], p0[4 * g + 1], 0, false); p8[g] = __builtin_amdgcn_cvt_pk_fp8_f32(p0[4 * g + 2], p0[4 * g + 3], w, true);
;     int u = __builtin_amdgcn_cvt_pk_fp8_f32(p1[4 * g], p1[4 * g + 1], 0, false); p8[4 + g] = __builtin_amdgcn_cvt_pk_fp8_f32(p1[4 * g + 2], p1[4 * g + 3], u, true); }
; }
; __device__ __forceinline__ void pv8(f32x16* o, const char* Vt, const v8i32 p8, int r32, int hi) {
;   const int sw = (r32 >> 2) & 3, a0 = r32 * 64 + (((hi * 2) ^ sw) << 4), a1 = r32 * 64 + (((hi * 2 + 1) ^ sw) << 4);
; #pragma unroll
;   for (int d0 = 0; d0 < 4; ++d0) {
;     const v8i32 vf = cat8(*reinterpret_cast<const v4i32*>(Vt + d0 * 2048 + a0), *reinterpret_cast<const v4i32*>(Vt + d0 * 2048 + a1));
;     o[d0] = __builtin_amdgcn_mfma_scale_f32_32x32x64_f8f6f4(p8, vf, o[d0], 0, 0, 0, 127, 0, 127); }
; }
; __device__ __forceinline__ void qkt9(f32x16& p0, f32x16& p1, const char* Kn, const char* Kr, const v8i32* qf, const float init, int r32, int hi) {
; #pragma unroll
;   for (int r = 0; r < 16; ++r) { p0[r] = init; p1[r] = init; }
; #pragma unroll
;   for (int s = 0; s < 2; ++s) { const int c0 = s * 4 + hi * 2;
;     const v8i32 a0 = cat8(*reinterpret_cast<const v4i32*>(Kn + KN8SW(r32, c0)), *reinterpret_cast<const v4i32*>(Kn + KN8SW(r32, c0 + 1)));
;     const v8i32 a1 = cat8(*reinterpret_cast<const v4i32*>(Kn + 4096 + KN8SW(r32, c0)), *reinterpret_cast<const v4i32*>(Kn + 4096 + KN8SW(r32, c0 + 1)));
;     p0 = __builtin_amdgcn_mfma_scale_f32_32x32x64_f8f6f4(a0, qf[s], p0, 0, 0, 0, 127, 0, 124);
;     p1 = __builtin_amdgcn_mfma_scale_f32_32x32x64_f8f6f4(a1, qf[s], p1, 0, 0, 0, 127, 0, 124); }
;   { const int c0 = hi * 2;
.Lmla_h3_cont:
	s_waitcnt lgkmcnt(0)
	s_barrier
	global_load_dwordx4 v[158:161], v176, s[18:19]
	global_load_dwordx4 v[162:165], v178, s[16:17]
	global_load_dwordx4 v[154:157], v[180:181], off
	ds_read_b128 v[114:117], v215 offset:51200
	ds_read_b128 v[118:121], v216 offset:51200
	ds_read_b128 v[222:225], v215 offset:55296
	ds_read_b128 v[226:229], v216 offset:55296
	v_exp_f32_e32 v0, v82
	v_exp_f32_e32 v177, v83
	v_exp_f32_e32 v179, v84
	v_exp_f32_e32 v254, v85
	v_add_f32_e32 v219, v0, v177
	v_cvt_pk_fp8_f32 v246, v0, v177
	v_add_f32_e32 v219, v179, v219
	v_add_f32_e32 v219, v254, v219
	v_cvt_pk_fp8_f32 v246, v179, v254 op_sel:[0,0,1]
	s_waitcnt lgkmcnt(2)
	v_mfma_scale_f32_32x32x64_f8f6f4 v[114:129], v[114:121], v[146:153], v[230:245], v194, v193 op_sel_hi:[0,0,0]
	v_exp_f32_e32 v0, v86
	v_exp_f32_e32 v177, v87
	v_exp_f32_e32 v179, v88
	v_exp_f32_e32 v254, v89
	v_add_f32_e32 v219, v0, v219
	v_add_f32_e32 v219, v177, v219
	v_cvt_pk_fp8_f32 v247, v0, v177
	v_add_f32_e32 v219, v179, v219
	v_add_f32_e32 v219, v254, v219
	v_cvt_pk_fp8_f32 v247, v179, v254 op_sel:[0,0,1]
	ds_read_b128 v[82:85], v213 offset:51200
	ds_read_b128 v[86:89], v214 offset:51200
	s_waitcnt lgkmcnt(2)
	v_mfma_scale_f32_32x32x64_f8f6f4 v[98:113], v[222:229], v[146:153], v[230:245], v194, v193 op_sel_hi:[0,0,0]
	ds_read_b128 v[222:225], v213 offset:55296
	ds_read_b128 v[226:229], v214 offset:55296
	v_exp_f32_e32 v0, v90
	v_exp_f32_e32 v177, v91
	v_exp_f32_e32 v179, v92
	v_exp_f32_e32 v254, v93
	v_add_f32_e32 v219, v0, v219
	v_add_f32_e32 v219, v177, v219
	v_cvt_pk_fp8_f32 v248, v0, v177
	v_add_f32_e32 v219, v179, v219
	v_add_f32_e32 v219, v254, v219
	v_cvt_pk_fp8_f32 v248, v179, v254 op_sel:[0,0,1]
	v_exp_f32_e32 v0, v94
	v_exp_f32_e32 v177, v95
	v_exp_f32_e32 v179, v96
	v_exp_f32_e32 v254, v97
	v_add_f32_e32 v219, v0, v219
	v_add_f32_e32 v219, v177, v219
	v_cvt_pk_fp8_f32 v249, v0, v177
	v_add_f32_e32 v219, v179, v219
	v_add_f32_e32 v219, v254, v219
	v_cvt_pk_fp8_f32 v249, v179, v254 op_sel:[0,0,1]
	ds_read_b128 v[90:93], v185 offset:59392
	ds_read_b128 v[94:97], v186 offset:59392
	s_waitcnt lgkmcnt(4)
	v_mfma_scale_f32_32x32x64_f8f6f4 v[114:129], v[82:89], v[138:145], v[114:129], v194, v193 op_sel_hi:[0,0,0]
	v_exp_f32_e32 v0, v66
	v_exp_f32_e32 v177, v67
	v_exp_f32_e32 v179, v68
	v_exp_f32_e32 v254, v69
	v_add_f32_e32 v219, v0, v219
	v_add_f32_e32 v219, v177, v219
	v_cvt_pk_fp8_f32 v250, v0, v177
	v_add_f32_e32 v219, v179, v219
	v_add_f32_e32 v219, v254, v219
	v_cvt_pk_fp8_f32 v250, v179, v254 op_sel:[0,0,1]
	s_waitcnt lgkmcnt(2)
	v_mfma_scale_f32_32x32x64_f8f6f4 v[98:113], v[222:229], v[138:145], v[98:113], v194, v193 op_sel_hi:[0,0,0]
	ds_read_b128 v[222:225], v185 offset:61440
	ds_read_b128 v[226:229], v186 offset:61440
	v_exp_f32_e32 v0, v70
	v_exp_f32_e32 v177, v71
	v_exp_f32_e32 v179, v72
	v_exp_f32_e32 v254, v73
	v_add_f32_e32 v219, v0, v219
	v_add_f32_e32 v219, v177, v219
	v_cvt_pk_fp8_f32 v251, v0, v177
	v_add_f32_e32 v219, v179, v219
	v_add_f32_e32 v219, v254, v219
	v_cvt_pk_fp8_f32 v251, v179, v254 op_sel:[0,0,1]
	v_exp_f32_e32 v0, v74
	v_exp_f32_e32 v177, v75
	v_exp_f32_e32 v179, v76
	v_exp_f32_e32 v254, v77
	v_add_f32_e32 v219, v0, v219
	v_add_f32_e32 v219, v177, v219
	v_cvt_pk_fp8_f32 v252, v0, v177
	v_add_f32_e32 v219, v179, v219
	v_add_f32_e32 v219, v254, v219
	v_cvt_pk_fp8_f32 v252, v179, v254 op_sel:[0,0,1]
	s_waitcnt lgkmcnt(2)
	v_mfma_scale_f32_32x32x64_f8f6f4 v[114:129], v[90:97], v[130:137], v[114:129], v194, v193 op_sel_hi:[0,0,0]
	v_exp_f32_e32 v0, v78
	v_exp_f32_e32 v177, v79
	v_exp_f32_e32 v179, v80
	v_exp_f32_e32 v254, v81
	v_add_f32_e32 v219, v0, v219
	v_add_f32_e32 v219, v177, v219
	v_cvt_pk_fp8_f32 v253, v0, v177
	v_add_f32_e32 v219, v179, v219
	v_add_f32_e32 v219, v254, v219
	v_cvt_pk_fp8_f32 v253, v179, v254 op_sel:[0,0,1]
	ds_read_b128 v[90:93], v185 offset:8192
	ds_read_b128 v[94:97], v186 offset:8192
	ds_read_b128 v[82:85], v185 offset:10240
	ds_read_b128 v[86:89], v186 offset:10240
	ds_read_b128 v[74:77], v185 offset:12288
	ds_read_b128 v[78:81], v186 offset:12288
	ds_read_b128 v[66:69], v185 offset:14336
	ds_read_b128 v[70:73], v186 offset:14336
	s_waitcnt lgkmcnt(8)
	v_mfma_scale_f32_32x32x64_f8f6f4 v[98:113], v[222:229], v[130:137], v[98:113], v194, v193 op_sel_hi:[0,0,0]
	v_mov_b32_e32 v0, v219
	s_nop 1
	v_permlane32_swap_b32_e32 v219, v0
	v_add_f32_e32 v219, v219, v0
	v_fma_f32 v209, v209, v218, v219
	v_add_u32_e32 v176, 0x2000, v176
	v_add_u32_e32 v178, 0x20000, v178
	s_mov_b64 s[20:21], 0x1000
	v_lshl_add_u64 v[180:181], v[180:181], 0, s[20:21]
	v_max_f32_e32 v177, v114, v115
	v_max3_f32 v177, v177, v116, v117
	v_max3_f32 v177, v177, v118, v119
	v_max3_f32 v177, v177, v120, v121
	v_max3_f32 v177, v177, v122, v123
	v_max3_f32 v177, v177, v124, v125
	v_max3_f32 v177, v177, v126, v127
	v_max3_f32 v177, v177, v128, v129
	s_waitcnt lgkmcnt(6)
	v_mfma_scale_f32_32x32x64_f8f6f4 v[50:65], v[246:253], v[90:97], v[50:65], v194, v194 op_sel_hi:[0,0,0]
	v_max_f32_e32 v0, v98, v99
	v_max3_f32 v0, v0, v100, v101
	v_max3_f32 v0, v0, v102, v103
	s_waitcnt lgkmcnt(4)
	v_mfma_scale_f32_32x32x64_f8f6f4 v[34:49], v[246:253], v[82:89], v[34:49], v194, v194 op_sel_hi:[0,0,0]
	v_max3_f32 v0, v0, v104, v105
	v_max3_f32 v0, v0, v106, v107
	v_max3_f32 v0, v0, v108, v109
	s_waitcnt lgkmcnt(2)
	v_mfma_scale_f32_32x32x64_f8f6f4 v[18:33], v[246:253], v[74:81], v[18:33], v194, v194 op_sel_hi:[0,0,0]
	v_max3_f32 v0, v0, v110, v111
	v_max3_f32 v0, v0, v112, v113
	v_max_f32_e32 v177, v177, v0
	v_mov_b32_e32 v0, v177
	v_mov_b32_e32 v221, 1.0
	s_waitcnt lgkmcnt(0)
	v_mfma_scale_f32_32x32x64_f8f6f4 v[2:17], v[246:253], v[66:73], v[2:17], v194, v194 op_sel_hi:[0,0,0]
	s_waitcnt vmcnt(0)
	ds_write_b128 v210, v[158:161]
	ds_write_b128 v211, v[162:165] offset:16384
	ds_write_b128 v212, v[154:157] offset:32768
	v_permlane32_swap_b32_e32 v177, v0
	v_max_f32_e32 v177, v177, v0
	v_cmp_ge_f32_e32 vcc, s90, v177
	s_cmp_eq_u64 vcc, exec
	s_cbranch_scc0 .Lmla_h4_newmax
; __device__ __forceinline__ void finishSM9(f32x16& p0, f32x16& p1, float alpha, float& l_reg, v8i32& p8) {
; #pragma unroll
;   for (int r = 0; r < 16; ++r) { p0[r] = __builtin_amdgcn_exp2f(p0[r]); p1[r] = __builtin_amdgcn_exp2f(p1[r]); }
;   float ps = 0;
; #pragma unroll
;   for (int r = 0; r < 16; ++r) ps += p0[r];
; #pragma unroll
;   for (int r = 0; r < 16; ++r) ps += p1[r];
;   { auto rr = __builtin_amdgcn_permlane32_swap(__float_as_uint(ps), __float_as_uint(ps), false, false);
;     ps = __uint_as_float(rr[0]) + __uint_as_float(rr[1]); }
;   l_reg = l_reg * alpha + ps;
; #pragma unroll
;   for (int g = 0; g < 4; ++g) {
;     int w = __builtin_amdgcn_cvt_pk_fp8_f32(p0[4 * g], p0[4 * g + 1], 0, false); p8[g] = __builtin_amdgcn_cvt_pk_fp8_f32(p0[4 * g + 2], p0[4 * g + 3], w, true);
;     int u = __builtin_amdgcn_cvt_pk_fp8_f32(p1[4 * g], p1[4 * g + 1], 0, false); p8[4 + g] = __builtin_amdgcn_cvt_pk_fp8_f32(p1[4 * g + 2], p1[4 * g + 3], u, true); }
; }
; __device__ __forceinline__ void pv8(f32x16* o, const char* Vt, const v8i32 p8, int r32, int hi) {
;   const int sw = (r32 >> 2) & 3, a0 = r32 * 64 + (((hi * 2) ^ sw) << 4), a1 = r32 * 64 + (((hi * 2 + 1) ^ sw) << 4);
; #pragma unroll
;   for (int d0 = 0; d0 < 4; ++d0) {
;     const v8i32 vf = cat8(*reinterpret_cast<const v4i32*>(Vt + d0 * 2048 + a0), *reinterpret_cast<const v4i32*>(Vt + d0 * 2048 + a1));
;     o[d0] = __builtin_amdgcn_mfma_scale_f32_32x32x64_f8f6f4(p8, vf, o[d0], 0, 0, 0, 127, 0, 127); }
; }
; __device__ __forceinline__ void qkt9(f32x16& p0, f32x16& p1, const char* Kn, const char* Kr, const v8i32* qf, const float init, int r32, int hi) {
; #pragma unroll
;   for (int r = 0; r < 16; ++r) { p0[r] = init; p1[r] = init; }
; #pragma unroll
;   for (int s = 0; s < 2; ++s) { const int c0 = s * 4 + hi * 2;
;     const v8i32 a0 = cat8(*reinterpret_cast<const v4i32*>(Kn + KN8SW(r32, c0)), *reinterpret_cast<const v4i32*>(Kn + KN8SW(r32, c0 + 1)));
;     const v8i32 a1 = cat8(*reinterpret_cast<const v4i32*>(Kn + 4096 + KN8SW(r32, c0)), *reinterpret_cast<const v4i32*>(Kn + 4096 + KN8SW(r32, c0 + 1)));
;     p0 = __builtin_amdgcn_mfma_scale_f32_32x32x64_f8f6f4(a0, qf[s], p0, 0, 0, 0, 127, 0, 124);
;     p1 = __builtin_amdgcn_mfma_scale_f32_32x32x64_f8f6f4(a1, qf[s], p1, 0, 0, 0, 127, 0, 124); }
;   { const int c0 = hi * 2;
.Lmla_h4_cont:
	s_waitcnt lgkmcnt(0)
	s_barrier
	global_load_dwordx4 v[158:161], v176, s[18:19]
	global_load_dwordx4 v[162:165], v178, s[16:17]
	global_load_dwordx4 v[154:157], v[180:181], off
	ds_read_b128 v[82:85], v215 offset:16384
	ds_read_b128 v[86:89], v216 offset:16384
	ds_read_b128 v[222:225], v215 offset:20480
	ds_read_b128 v[226:229], v216 offset:20480
	v_exp_f32_e32 v0, v114
	v_exp_f32_e32 v177, v115
	v_exp_f32_e32 v179, v116
	v_exp_f32_e32 v254, v117
	v_add_f32_e32 v219, v0, v177
	v_cvt_pk_fp8_f32 v246, v0, v177
	v_add_f32_e32 v219, v179, v219
	v_add_f32_e32 v219, v254, v219
	v_cvt_pk_fp8_f32 v246, v179, v254 op_sel:[0,0,1]
	s_waitcnt lgkmcnt(2)
	v_mfma_scale_f32_32x32x64_f8f6f4 v[82:97], v[82:89], v[146:153], v[230:245], v194, v193 op_sel_hi:[0,0,0]
	v_exp_f32_e32 v0, v118
	v_exp_f32_e32 v177, v119
	v_exp_f32_e32 v179, v120
	v_exp_f32_e32 v254, v121
	v_add_f32_e32 v219, v0, v219
	v_add_f32_e32 v219, v177, v219
	v_cvt_pk_fp8_f32 v247, v0, v177
	v_add_f32_e32 v219, v179, v219
	v_add_f32_e32 v219, v254, v219
	v_cvt_pk_fp8_f32 v247, v179, v254 op_sel:[0,0,1]
	ds_read_b128 v[114:117], v213 offset:16384
	ds_read_b128 v[118:121], v214 offset:16384
	s_waitcnt lgkmcnt(2)
	v_mfma_scale_f32_32x32x64_f8f6f4 v[66:81], v[222:229], v[146:153], v[230:245], v194, v193 op_sel_hi:[0,0,0]
	ds_read_b128 v[222:225], v213 offset:20480
	ds_read_b128 v[226:229], v214 offset:20480
	v_exp_f32_e32 v0, v122
	v_exp_f32_e32 v177, v123
	v_exp_f32_e32 v179, v124
	v_exp_f32_e32 v254, v125
	v_add_f32_e32 v219, v0, v219
	v_add_f32_e32 v219, v177, v219
	v_cvt_pk_fp8_f32 v248, v0, v177
	v_add_f32_e32 v219, v179, v219
	v_add_f32_e32 v219, v254, v219
	v_cvt_pk_fp8_f32 v248, v179, v254 op_sel:[0,0,1]
	v_exp_f32_e32 v0, v126
	v_exp_f32_e32 v177, v127
	v_exp_f32_e32 v179, v128
	v_exp_f32_e32 v254, v129
	v_add_f32_e32 v219, v0, v219
	v_add_f32_e32 v219, v177, v219
	v_cvt_pk_fp8_f32 v249, v0, v177
	v_add_f32_e32 v219, v179, v219
	v_add_f32_e32 v219, v254, v219
	v_cvt_pk_fp8_f32 v249, v179, v254 op_sel:[0,0,1]
	ds_read_b128 v[122:125], v185 offset:32768
	ds_read_b128 v[126:129], v186 offset:32768
	s_waitcnt lgkmcnt(4)
	v_mfma_scale_f32_32x32x64_f8f6f4 v[82:97], v[114:121], v[138:145], v[82:97], v194, v193 op_sel_hi:[0,0,0]
	v_exp_f32_e32 v0, v98
	v_exp_f32_e32 v177, v99
	v_exp_f32_e32 v179, v100
	v_exp_f32_e32 v254, v101
	v_add_f32_e32 v219, v0, v219
	v_add_f32_e32 v219, v177, v219
	v_cvt_pk_fp8_f32 v250, v0, v177
	v_add_f32_e32 v219, v179, v219
	v_add_f32_e32 v219, v254, v219
	v_cvt_pk_fp8_f32 v250, v179, v254 op_sel:[0,0,1]
	s_waitcnt lgkmcnt(2)
	v_mfma_scale_f32_32x32x64_f8f6f4 v[66:81], v[222:229], v[138:145], v[66:81], v194, v193 op_sel_hi:[0,0,0]
	ds_read_b128 v[222:225], v185 offset:34816
	ds_read_b128 v[226:229], v186 offset:34816
	v_exp_f32_e32 v0, v102
	v_exp_f32_e32 v177, v103
	v_exp_f32_e32 v179, v104
	v_exp_f32_e32 v254, v105
	v_add_f32_e32 v219, v0, v219
	v_add_f32_e32 v219, v177, v219
	v_cvt_pk_fp8_f32 v251, v0, v177
	v_add_f32_e32 v219, v179, v219
	v_add_f32_e32 v219, v254, v219
	v_cvt_pk_fp8_f32 v251, v179, v254 op_sel:[0,0,1]
	v_exp_f32_e32 v0, v106
	v_exp_f32_e32 v177, v107
	v_exp_f32_e32 v179, v108
	v_exp_f32_e32 v254, v109
	v_add_f32_e32 v219, v0, v219
	v_add_f32_e32 v219, v177, v219
	v_cvt_pk_fp8_f32 v252, v0, v177
	v_add_f32_e32 v219, v179, v219
	v_add_f32_e32 v219, v254, v219
	v_cvt_pk_fp8_f32 v252, v179, v254 op_sel:[0,0,1]
	s_waitcnt lgkmcnt(2)
	v_mfma_scale_f32_32x32x64_f8f6f4 v[82:97], v[122:129], v[130:137], v[82:97], v194, v193 op_sel_hi:[0,0,0]
	v_exp_f32_e32 v0, v110
	v_exp_f32_e32 v177, v111
	v_exp_f32_e32 v179, v112
	v_exp_f32_e32 v254, v113
	v_add_f32_e32 v219, v0, v219
	v_add_f32_e32 v219, v177, v219
	v_cvt_pk_fp8_f32 v253, v0, v177
	v_add_f32_e32 v219, v179, v219
	v_add_f32_e32 v219, v254, v219
	v_cvt_pk_fp8_f32 v253, v179, v254 op_sel:[0,0,1]
	ds_read_b128 v[122:125], v185 offset:43008
	ds_read_b128 v[126:129], v186 offset:43008
	ds_read_b128 v[114:117], v185 offset:45056
	ds_read_b128 v[118:121], v186 offset:45056
	ds_read_b128 v[106:109], v185 offset:47104
	ds_read_b128 v[110:113], v186 offset:47104
	ds_read_b128 v[98:101], v185 offset:49152
	ds_read_b128 v[102:105], v186 offset:49152
	s_waitcnt lgkmcnt(8)
	v_mfma_scale_f32_32x32x64_f8f6f4 v[66:81], v[222:229], v[130:137], v[66:81], v194, v193 op_sel_hi:[0,0,0]
	v_mov_b32_e32 v0, v219
	s_nop 1
	v_permlane32_swap_b32_e32 v219, v0
	v_add_f32_e32 v219, v219, v0
	v_fma_f32 v209, v209, v221, v219
	v_add_u32_e32 v176, 0x2000, v176
	v_add_u32_e32 v178, 0x20000, v178
	s_mov_b64 s[20:21], 0x1000
	v_lshl_add_u64 v[180:181], v[180:181], 0, s[20:21]
	v_max_f32_e32 v177, v82, v83
	v_max3_f32 v177, v177, v84, v85
	v_max3_f32 v177, v177, v86, v87
	v_max3_f32 v177, v177, v88, v89
	v_max3_f32 v177, v177, v90, v91
	v_max3_f32 v177, v177, v92, v93
	v_max3_f32 v177, v177, v94, v95
	v_max3_f32 v177, v177, v96, v97
	s_waitcnt lgkmcnt(6)
	v_mfma_scale_f32_32x32x64_f8f6f4 v[50:65], v[246:253], v[122:129], v[50:65], v194, v194 op_sel_hi:[0,0,0]
	v_max_f32_e32 v0, v66, v67
	v_max3_f32 v0, v0, v68, v69
	v_max3_f32 v0, v0, v70, v71
	s_waitcnt lgkmcnt(4)
	v_mfma_scale_f32_32x32x64_f8f6f4 v[34:49], v[246:253], v[114:121], v[34:49], v194, v194 op_sel_hi:[0,0,0]
	v_max3_f32 v0, v0, v72, v73
	v_max3_f32 v0, v0, v74, v75
	v_max3_f32 v0, v0, v76, v77
	s_waitcnt lgkmcnt(2)
	v_mfma_scale_f32_32x32x64_f8f6f4 v[18:33], v[246:253], v[106:113], v[18:33], v194, v194 op_sel_hi:[0,0,0]
	v_max3_f32 v0, v0, v78, v79
	v_max3_f32 v0, v0, v80, v81
	v_max_f32_e32 v177, v177, v0
	v_mov_b32_e32 v0, v177
	v_mov_b32_e32 v218, 1.0
	s_waitcnt lgkmcnt(0)
	v_mfma_scale_f32_32x32x64_f8f6f4 v[2:17], v[246:253], v[98:105], v[2:17], v194, v194 op_sel_hi:[0,0,0]
	s_waitcnt vmcnt(0)
	ds_write_b128 v210, v[158:161] offset:8192
	ds_write_b128 v211, v[162:165] offset:24576
	ds_write_b128 v212, v[154:157] offset:36864
	v_permlane32_swap_b32_e32 v177, v0
	v_max_f32_e32 v177, v177, v0
	v_cmp_ge_f32_e32 vcc, s90, v177
	s_cmp_eq_u64 vcc, exec
	s_cbranch_scc0 .Lmla_h5_newmax
; __device__ __forceinline__ void finishSM9(f32x16& p0, f32x16& p1, float alpha, float& l_reg, v8i32& p8) {
; #pragma unroll
;   for (int r = 0; r < 16; ++r) { p0[r] = __builtin_amdgcn_exp2f(p0[r]); p1[r] = __builtin_amdgcn_exp2f(p1[r]); }
;   float ps = 0;
; #pragma unroll
;   for (int r = 0; r < 16; ++r) ps += p0[r];
; #pragma unroll
;   for (int r = 0; r < 16; ++r) ps += p1[r];
;   { auto rr = __builtin_amdgcn_permlane32_swap(__float_as_uint(ps), __float_as_uint(ps), false, false);
;     ps = __uint_as_float(rr[0]) + __uint_as_float(rr[1]); }
;   l_reg = l_reg * alpha + ps;
; #pragma unroll
;   for (int g = 0; g < 4; ++g) {
;     int w = __builtin_amdgcn_cvt_pk_fp8_f32(p0[4 * g], p0[4 * g + 1], 0, false); p8[g] = __builtin_amdgcn_cvt_pk_fp8_f32(p0[4 * g + 2], p0[4 * g + 3], w, true);
;     int u = __builtin_amdgcn_cvt_pk_fp8_f32(p1[4 * g], p1[4 * g + 1], 0, false); p8[4 + g] = __builtin_amdgcn_cvt_pk_fp8_f32(p1[4 * g + 2], p1[4 * g + 3], u, true); }
; }
; __device__ __forceinline__ void pv8(f32x16* o, const char* Vt, const v8i32 p8, int r32, int hi) {
;   const int sw = (r32 >> 2) & 3, a0 = r32 * 64 + (((hi * 2) ^ sw) << 4), a1 = r32 * 64 + (((hi * 2 + 1) ^ sw) << 4);
; #pragma unroll
;   for (int d0 = 0; d0 < 4; ++d0) {
;     const v8i32 vf = cat8(*reinterpret_cast<const v4i32*>(Vt + d0 * 2048 + a0), *reinterpret_cast<const v4i32*>(Vt + d0 * 2048 + a1));
;     o[d0] = __builtin_amdgcn_mfma_scale_f32_32x32x64_f8f6f4(p8, vf, o[d0], 0, 0, 0, 127, 0, 127); }
; }
; __device__ __forceinline__ void qkt9(f32x16& p0, f32x16& p1, const char* Kn, const char* Kr, const v8i32* qf, const float init, int r32, int hi) {
; #pragma unroll
;   for (int r = 0; r < 16; ++r) { p0[r] = init; p1[r] = init; }
; #pragma unroll
;   for (int s = 0; s < 2; ++s) { const int c0 = s * 4 + hi * 2;
;     const v8i32 a0 = cat8(*reinterpret_cast<const v4i32*>(Kn + KN8SW(r32, c0)), *reinterpret_cast<const v4i32*>(Kn + KN8SW(r32, c0 + 1)));
;     const v8i32 a1 = cat8(*reinterpret_cast<const v4i32*>(Kn + 4096 + KN8SW(r32, c0)), *reinterpret_cast<const v4i32*>(Kn + 4096 + KN8SW(r32, c0 + 1)));
;     p0 = __builtin_amdgcn_mfma_scale_f32_32x32x64_f8f6f4(a0, qf[s], p0, 0, 0, 0, 127, 0, 124);
;     p1 = __builtin_amdgcn_mfma_scale_f32_32x32x64_f8f6f4(a1, qf[s], p1, 0, 0, 0, 127, 0, 124); }
;   { const int c0 = hi * 2;
.Lmla_h5_cont:
	s_waitcnt lgkmcnt(0)
	s_barrier
	s_add_i32 s30, s30, 1
	s_cmpk_lt_u32 s30, 42
	s_cbranch_scc1 .LBB0_1321
	global_load_dwordx4 v[158:161], v176, s[18:19]
	global_load_dwordx4 v[162:165], v178, s[16:17]
	global_load_dwordx4 v[154:157], v[180:181], off
	ds_read_b128 v[114:117], v215 offset:24576
	ds_read_b128 v[118:121], v216 offset:24576
	ds_read_b128 v[222:225], v215 offset:28672
	ds_read_b128 v[226:229], v216 offset:28672
	v_exp_f32_e32 v0, v82
	v_exp_f32_e32 v177, v83
	v_exp_f32_e32 v179, v84
	v_exp_f32_e32 v254, v85
	v_add_f32_e32 v219, v0, v177
	v_cvt_pk_fp8_f32 v246, v0, v177
	v_add_f32_e32 v219, v179, v219
	v_add_f32_e32 v219, v254, v219
	v_cvt_pk_fp8_f32 v246, v179, v254 op_sel:[0,0,1]
	s_waitcnt lgkmcnt(2)
	v_mfma_scale_f32_32x32x64_f8f6f4 v[114:129], v[114:121], v[146:153], v[230:245], v194, v193 op_sel_hi:[0,0,0]
	v_exp_f32_e32 v0, v86
	v_exp_f32_e32 v177, v87
	v_exp_f32_e32 v179, v88
	v_exp_f32_e32 v254, v89
	v_add_f32_e32 v219, v0, v219
	v_add_f32_e32 v219, v177, v219
	v_cvt_pk_fp8_f32 v247, v0, v177
	v_add_f32_e32 v219, v179, v219
	v_add_f32_e32 v219, v254, v219
	v_cvt_pk_fp8_f32 v247, v179, v254 op_sel:[0,0,1]
	ds_read_b128 v[82:85], v213 offset:24576
	ds_read_b128 v[86:89], v214 offset:24576
	s_waitcnt lgkmcnt(2)
	v_mfma_scale_f32_32x32x64_f8f6f4 v[98:113], v[222:229], v[146:153], v[230:245], v194, v193 op_sel_hi:[0,0,0]
	ds_read_b128 v[222:225], v213 offset:28672
	ds_read_b128 v[226:229], v214 offset:28672
	v_exp_f32_e32 v0, v90
	v_exp_f32_e32 v177, v91
	v_exp_f32_e32 v179, v92
	v_exp_f32_e32 v254, v93
	v_add_f32_e32 v219, v0, v219
	v_add_f32_e32 v219, v177, v219
	v_cvt_pk_fp8_f32 v248, v0, v177
	v_add_f32_e32 v219, v179, v219
	v_add_f32_e32 v219, v254, v219
	v_cvt_pk_fp8_f32 v248, v179, v254 op_sel:[0,0,1]
	v_exp_f32_e32 v0, v94
	v_exp_f32_e32 v177, v95
	v_exp_f32_e32 v179, v96
	v_exp_f32_e32 v254, v97
	v_add_f32_e32 v219, v0, v219
	v_add_f32_e32 v219, v177, v219
	v_cvt_pk_fp8_f32 v249, v0, v177
	v_add_f32_e32 v219, v179, v219
	v_add_f32_e32 v219, v254, v219
	v_cvt_pk_fp8_f32 v249, v179, v254 op_sel:[0,0,1]
	ds_read_b128 v[90:93], v185 offset:36864
	ds_read_b128 v[94:97], v186 offset:36864
	s_waitcnt lgkmcnt(4)
	v_mfma_scale_f32_32x32x64_f8f6f4 v[114:129], v[82:89], v[138:145], v[114:129], v194, v193 op_sel_hi:[0,0,0]
	v_exp_f32_e32 v0, v66
	v_exp_f32_e32 v177, v67
	v_exp_f32_e32 v179, v68
	v_exp_f32_e32 v254, v69
	v_add_f32_e32 v219, v0, v219
	v_add_f32_e32 v219, v177, v219
	v_cvt_pk_fp8_f32 v250, v0, v177
	v_add_f32_e32 v219, v179, v219
	v_add_f32_e32 v219, v254, v219
	v_cvt_pk_fp8_f32 v250, v179, v254 op_sel:[0,0,1]
	s_waitcnt lgkmcnt(2)
	v_mfma_scale_f32_32x32x64_f8f6f4 v[98:113], v[222:229], v[138:145], v[98:113], v194, v193 op_sel_hi:[0,0,0]
	ds_read_b128 v[222:225], v185 offset:38912
	ds_read_b128 v[226:229], v186 offset:38912
	v_exp_f32_e32 v0, v70
	v_exp_f32_e32 v177, v71
	v_exp_f32_e32 v179, v72
	v_exp_f32_e32 v254, v73
	v_add_f32_e32 v219, v0, v219
	v_add_f32_e32 v219, v177, v219
	v_cvt_pk_fp8_f32 v251, v0, v177
	v_add_f32_e32 v219, v179, v219
	v_add_f32_e32 v219, v254, v219
	v_cvt_pk_fp8_f32 v251, v179, v254 op_sel:[0,0,1]
	v_exp_f32_e32 v0, v74
	v_exp_f32_e32 v177, v75
	v_exp_f32_e32 v179, v76
	v_exp_f32_e32 v254, v77
	v_add_f32_e32 v219, v0, v219
	v_add_f32_e32 v219, v177, v219
	v_cvt_pk_fp8_f32 v252, v0, v177
	v_add_f32_e32 v219, v179, v219
	v_add_f32_e32 v219, v254, v219
	v_cvt_pk_fp8_f32 v252, v179, v254 op_sel:[0,0,1]
	s_waitcnt lgkmcnt(2)
	v_mfma_scale_f32_32x32x64_f8f6f4 v[114:129], v[90:97], v[130:137], v[114:129], v194, v193 op_sel_hi:[0,0,0]
	v_exp_f32_e32 v0, v78
	v_exp_f32_e32 v177, v79
	v_exp_f32_e32 v179, v80
	v_exp_f32_e32 v254, v81
	v_add_f32_e32 v219, v0, v219
	v_add_f32_e32 v219, v177, v219
	v_cvt_pk_fp8_f32 v253, v0, v177
	v_add_f32_e32 v219, v179, v219
	v_add_f32_e32 v219, v254, v219
	v_cvt_pk_fp8_f32 v253, v179, v254 op_sel:[0,0,1]
	ds_read_b128 v[90:93], v185 offset:0
	ds_read_b128 v[94:97], v186 offset:0
	ds_read_b128 v[82:85], v185 offset:2048
	ds_read_b128 v[86:89], v186 offset:2048
	ds_read_b128 v[74:77], v185 offset:4096
	ds_read_b128 v[78:81], v186 offset:4096
	ds_read_b128 v[66:69], v185 offset:6144
	ds_read_b128 v[70:73], v186 offset:6144
	s_waitcnt lgkmcnt(8)
	v_mfma_scale_f32_32x32x64_f8f6f4 v[98:113], v[222:229], v[130:137], v[98:113], v194, v193 op_sel_hi:[0,0,0]
	v_mov_b32_e32 v0, v219
	s_nop 1
	v_permlane32_swap_b32_e32 v219, v0
	v_add_f32_e32 v219, v219, v0
	v_fma_f32 v209, v209, v218, v219
	v_add_u32_e32 v176, 0x2000, v176
	v_add_u32_e32 v178, 0x20000, v178
	s_mov_b64 s[20:21], 0x1000
	v_lshl_add_u64 v[180:181], v[180:181], 0, s[20:21]
	v_max_f32_e32 v177, v114, v115
	v_max3_f32 v177, v177, v116, v117
	v_max3_f32 v177, v177, v118, v119
	v_max3_f32 v177, v177, v120, v121
	v_max3_f32 v177, v177, v122, v123
	v_max3_f32 v177, v177, v124, v125
	v_max3_f32 v177, v177, v126, v127
	v_max3_f32 v177, v177, v128, v129
	s_waitcnt lgkmcnt(6)
	v_mfma_scale_f32_32x32x64_f8f6f4 v[50:65], v[246:253], v[90:97], v[50:65], v194, v194 op_sel_hi:[0,0,0]
	v_max_f32_e32 v0, v98, v99
	v_max3_f32 v0, v0, v100, v101
	v_max3_f32 v0, v0, v102, v103
	s_waitcnt lgkmcnt(4)
	v_mfma_scale_f32_32x32x64_f8f6f4 v[34:49], v[246:253], v[82:89], v[34:49], v194, v194 op_sel_hi:[0,0,0]
	v_max3_f32 v0, v0, v104, v105
	v_max3_f32 v0, v0, v106, v107
	v_max3_f32 v0, v0, v108, v109
	s_waitcnt lgkmcnt(2)
	v_mfma_scale_f32_32x32x64_f8f6f4 v[18:33], v[246:253], v[74:81], v[18:33], v194, v194 op_sel_hi:[0,0,0]
	v_max3_f32 v0, v0, v110, v111
	v_max3_f32 v0, v0, v112, v113
	v_max_f32_e32 v177, v177, v0
	v_mov_b32_e32 v0, v177
	v_mov_b32_e32 v221, 1.0
	s_waitcnt lgkmcnt(0)
	v_mfma_scale_f32_32x32x64_f8f6f4 v[2:17], v[246:253], v[66:73], v[2:17], v194, v194 op_sel_hi:[0,0,0]
	s_waitcnt vmcnt(0)
	ds_write_b128 v210, v[158:161] offset:43008
	ds_write_b128 v211, v[162:165] offset:51200
	ds_write_b128 v212, v[154:157] offset:59392
	v_permlane32_swap_b32_e32 v177, v0
	v_max_f32_e32 v177, v177, v0
	v_cmp_ge_f32_e32 vcc, s90, v177
	s_cmp_eq_u64 vcc, exec
	s_cbranch_scc0 .Lmla_p0_newmax

; __device__ __forceinline__ void finishSM9(f32x16& p0, f32x16& p1, float alpha, float& l_reg, v8i32& p8) {
; #pragma unroll
;   for (int r = 0; r < 16; ++r) { p0[r] = __builtin_amdgcn_exp2f(p0[r]); p1[r] = __builtin_amdgcn_exp2f(p1[r]); }
;   float ps = 0;
; #pragma unroll
;   for (int r = 0; r < 16; ++r) ps += p0[r];
; #pragma unroll
;   for (int r = 0; r < 16; ++r) ps += p1[r];
;   { auto rr = __builtin_amdgcn_permlane32_swap(__float_as_uint(ps), __float_as_uint(ps), false, false);
;     ps = __uint_as_float(rr[0]) + __uint_as_float(rr[1]); }
;   l_reg = l_reg * alpha + ps;
; #pragma unroll
;   for (int g = 0; g < 4; ++g) {
;     int w = __builtin_amdgcn_cvt_pk_fp8_f32(p0[4 * g], p0[4 * g + 1], 0, false); p8[g] = __builtin_amdgcn_cvt_pk_fp8_f32(p0[4 * g + 2], p0[4 * g + 3], w, true);
;     int u = __builtin_amdgcn_cvt_pk_fp8_f32(p1[4 * g], p1[4 * g + 1], 0, false); p8[4 + g] = __builtin_amdgcn_cvt_pk_fp8_f32(p1[4 * g + 2], p1[4 * g + 3], u, true); }
; }
; __device__ __forceinline__ void pv8(f32x16* o, const char* Vt, const v8i32 p8, int r32, int hi) {
;   const int sw = (r32 >> 2) & 3, a0 = r32 * 64 + (((hi * 2) ^ sw) << 4), a1 = r32 * 64 + (((hi * 2 + 1) ^ sw) << 4);
; #pragma unroll
;   for (int d0 = 0; d0 < 4; ++d0) {
;     const v8i32 vf = cat8(*reinterpret_cast<const v4i32*>(Vt + d0 * 2048 + a0), *reinterpret_cast<const v4i32*>(Vt + d0 * 2048 + a1));
;     o[d0] = __builtin_amdgcn_mfma_scale_f32_32x32x64_f8f6f4(p8, vf, o[d0], 0, 0, 0, 127, 0, 127); }
; }
; __device__ __forceinline__ void qkt9(f32x16& p0, f32x16& p1, const char* Kn, const char* Kr, const v8i32* qf, const float init, int r32, int hi) {
; #pragma unroll
;   for (int r = 0; r < 16; ++r) { p0[r] = init; p1[r] = init; }
; #pragma unroll
;   for (int s = 0; s < 2; ++s) { const int c0 = s * 4 + hi * 2;
;     const v8i32 a0 = cat8(*reinterpret_cast<const v4i32*>(Kn + KN8SW(r32, c0)), *reinterpret_cast<const v4i32*>(Kn + KN8SW(r32, c0 + 1)));
;     const v8i32 a1 = cat8(*reinterpret_cast<const v4i32*>(Kn + 4096 + KN8SW(r32, c0)), *reinterpret_cast<const v4i32*>(Kn + 4096 + KN8SW(r32, c0 + 1)));
;     p0 = __builtin_amdgcn_mfma_scale_f32_32x32x64_f8f6f4(a0, qf[s], p0, 0, 0, 0, 127, 0, 124);
;     p1 = __builtin_amdgcn_mfma_scale_f32_32x32x64_f8f6f4(a1, qf[s], p1, 0, 0, 0, 127, 0, 124); }
;   { const int c0 = hi * 2;
.Lmla_stag_loop:
	ds_read_b128 v[114:117], v215 offset:24576
	ds_read_b128 v[118:121], v216 offset:24576
	ds_read_b128 v[222:225], v215 offset:28672
	ds_read_b128 v[226:229], v216 offset:28672
	v_exp_f32_e32 v0, v82
	v_exp_f32_e32 v177, v83
	v_exp_f32_e32 v179, v84
	v_exp_f32_e32 v254, v85
	v_add_f32_e32 v219, v0, v177
	v_cvt_pk_fp8_f32 v246, v0, v177
	v_add_f32_e32 v219, v179, v219
	v_add_f32_e32 v219, v254, v219
	v_cvt_pk_fp8_f32 v246, v179, v254 op_sel:[0,0,1]
	s_waitcnt lgkmcnt(2)
	v_mfma_scale_f32_32x32x64_f8f6f4 v[114:129], v[114:121], v[146:153], v[230:245], v194, v193 op_sel_hi:[0,0,0]
	v_exp_f32_e32 v0, v86
	v_exp_f32_e32 v177, v87
	v_exp_f32_e32 v179, v88
	v_exp_f32_e32 v254, v89
	v_add_f32_e32 v219, v0, v219
	v_add_f32_e32 v219, v177, v219
	v_cvt_pk_fp8_f32 v247, v0, v177
	v_add_f32_e32 v219, v179, v219
	v_add_f32_e32 v219, v254, v219
	v_cvt_pk_fp8_f32 v247, v179, v254 op_sel:[0,0,1]
	ds_read_b128 v[82:85], v213 offset:24576
	ds_read_b128 v[86:89], v214 offset:24576
	s_waitcnt lgkmcnt(2)
	v_mfma_scale_f32_32x32x64_f8f6f4 v[98:113], v[222:229], v[146:153], v[230:245], v194, v193 op_sel_hi:[0,0,0]
	ds_read_b128 v[222:225], v213 offset:28672
	ds_read_b128 v[226:229], v214 offset:28672
	v_exp_f32_e32 v0, v90
	v_exp_f32_e32 v177, v91
	v_exp_f32_e32 v179, v92
	v_exp_f32_e32 v254, v93
	v_add_f32_e32 v219, v0, v219
	v_add_f32_e32 v219, v177, v219
	v_cvt_pk_fp8_f32 v248, v0, v177
	v_add_f32_e32 v219, v179, v219
	v_add_f32_e32 v219, v254, v219
	v_cvt_pk_fp8_f32 v248, v179, v254 op_sel:[0,0,1]
	v_exp_f32_e32 v0, v94
	v_exp_f32_e32 v177, v95
	v_exp_f32_e32 v179, v96
	v_exp_f32_e32 v254, v97
	v_add_f32_e32 v219, v0, v219
	v_add_f32_e32 v219, v177, v219
	v_cvt_pk_fp8_f32 v249, v0, v177
	v_add_f32_e32 v219, v179, v219
	v_add_f32_e32 v219, v254, v219
	v_cvt_pk_fp8_f32 v249, v179, v254 op_sel:[0,0,1]
	ds_read_b128 v[90:93], v185 offset:36864
	ds_read_b128 v[94:97], v186 offset:36864
	s_waitcnt lgkmcnt(4)
	v_mfma_scale_f32_32x32x64_f8f6f4 v[114:129], v[82:89], v[138:145], v[114:129], v194, v193 op_sel_hi:[0,0,0]
	v_exp_f32_e32 v0, v66
	v_exp_f32_e32 v177, v67
	v_exp_f32_e32 v179, v68
	v_exp_f32_e32 v254, v69
	v_add_f32_e32 v219, v0, v219
	v_add_f32_e32 v219, v177, v219
	v_cvt_pk_fp8_f32 v250, v0, v177
	v_add_f32_e32 v219, v179, v219
	v_add_f32_e32 v219, v254, v219
	v_cvt_pk_fp8_f32 v250, v179, v254 op_sel:[0,0,1]
	s_waitcnt lgkmcnt(2)
	v_mfma_scale_f32_32x32x64_f8f6f4 v[98:113], v[222:229], v[138:145], v[98:113], v194, v193 op_sel_hi:[0,0,0]
	ds_read_b128 v[222:225], v185 offset:38912
	ds_read_b128 v[226:229], v186 offset:38912
	v_exp_f32_e32 v0, v70
	v_exp_f32_e32 v177, v71
	v_exp_f32_e32 v179, v72
	v_exp_f32_e32 v254, v73
	v_add_f32_e32 v219, v0, v219
	v_add_f32_e32 v219, v177, v219
	v_cvt_pk_fp8_f32 v251, v0, v177
	v_add_f32_e32 v219, v179, v219
	v_add_f32_e32 v219, v254, v219
	v_cvt_pk_fp8_f32 v251, v179, v254 op_sel:[0,0,1]
	v_exp_f32_e32 v0, v74
	v_exp_f32_e32 v177, v75
	v_exp_f32_e32 v179, v76
	v_exp_f32_e32 v254, v77
	v_add_f32_e32 v219, v0, v219
	v_add_f32_e32 v219, v177, v219
	v_cvt_pk_fp8_f32 v252, v0, v177
	v_add_f32_e32 v219, v179, v219
	v_add_f32_e32 v219, v254, v219
	v_cvt_pk_fp8_f32 v252, v179, v254 op_sel:[0,0,1]
	s_waitcnt lgkmcnt(2)
	v_mfma_scale_f32_32x32x64_f8f6f4 v[114:129], v[90:97], v[130:137], v[114:129], v194, v193 op_sel_hi:[0,0,0]
	v_exp_f32_e32 v0, v78
	v_exp_f32_e32 v177, v79
	v_exp_f32_e32 v179, v80
	v_exp_f32_e32 v254, v81
	v_add_f32_e32 v219, v0, v219
	v_add_f32_e32 v219, v177, v219
	v_cvt_pk_fp8_f32 v253, v0, v177
	v_add_f32_e32 v219, v179, v219
	v_add_f32_e32 v219, v254, v219
	v_cvt_pk_fp8_f32 v253, v179, v254 op_sel:[0,0,1]
	ds_read_b128 v[90:93], v185 offset:0
	ds_read_b128 v[94:97], v186 offset:0
	ds_read_b128 v[82:85], v185 offset:2048
	ds_read_b128 v[86:89], v186 offset:2048
	ds_read_b128 v[74:77], v185 offset:4096
	ds_read_b128 v[78:81], v186 offset:4096
	ds_read_b128 v[66:69], v185 offset:6144
	ds_read_b128 v[70:73], v186 offset:6144
	s_waitcnt lgkmcnt(8)
	v_mfma_scale_f32_32x32x64_f8f6f4 v[98:113], v[222:229], v[130:137], v[98:113], v194, v193 op_sel_hi:[0,0,0]
	v_mov_b32_e32 v0, v219
	s_nop 1
	v_permlane32_swap_b32_e32 v219, v0
	v_add_f32_e32 v219, v219, v0
	v_fma_f32 v209, v209, v218, v219
	s_waitcnt vmcnt(0)
	ds_write_b128 v210, v[158:161] offset:43008
	ds_write_b128 v211, v[162:165] offset:51200
	s_waitcnt lgkmcnt(0)
	s_barrier
	global_load_dwordx4 v[158:161], v176, s[18:19]
	global_load_dwordx4 v[162:165], v178, s[16:17]
	v_add_u32_e32 v176, 0x2000, v176
	v_add_u32_e32 v178, 0x20000, v178
	v_max_f32_e32 v177, v114, v115
	v_max3_f32 v177, v177, v116, v117
	v_max3_f32 v177, v177, v118, v119
	v_max3_f32 v177, v177, v120, v121
	v_max3_f32 v177, v177, v122, v123
	v_max3_f32 v177, v177, v124, v125
	v_max3_f32 v177, v177, v126, v127
	v_max3_f32 v177, v177, v128, v129
	s_waitcnt lgkmcnt(6)
	v_mfma_scale_f32_32x32x64_f8f6f4 v[50:65], v[246:253], v[90:97], v[50:65], v194, v194 op_sel_hi:[0,0,0]
	v_max_f32_e32 v0, v98, v99
	v_max3_f32 v0, v0, v100, v101
	v_max3_f32 v0, v0, v102, v103
	s_waitcnt lgkmcnt(4)
	v_mfma_scale_f32_32x32x64_f8f6f4 v[34:49], v[246:253], v[82:89], v[34:49], v194, v194 op_sel_hi:[0,0,0]
	v_max3_f32 v0, v0, v104, v105
	v_max3_f32 v0, v0, v106, v107
	v_max3_f32 v0, v0, v108, v109
	s_waitcnt lgkmcnt(2)
	v_mfma_scale_f32_32x32x64_f8f6f4 v[18:33], v[246:253], v[74:81], v[18:33], v194, v194 op_sel_hi:[0,0,0]
	v_max3_f32 v0, v0, v110, v111
	v_max3_f32 v0, v0, v112, v113
	v_max_f32_e32 v177, v177, v0
	v_mov_b32_e32 v0, v177
	v_mov_b32_e32 v221, 1.0
	s_waitcnt lgkmcnt(0)
	v_mfma_scale_f32_32x32x64_f8f6f4 v[2:17], v[246:253], v[66:73], v[2:17], v194, v194 op_sel_hi:[0,0,0]
	s_nop 0
	v_permlane32_swap_b32_e32 v177, v0
	v_max_f32_e32 v177, v177, v0
	v_cmp_ge_f32_e32 vcc, s90, v177
	s_cmp_eq_u64 vcc, exec
	s_cbranch_scc0 .Lmla_s0_newmax
; __device__ __forceinline__ void finishSM9(f32x16& p0, f32x16& p1, float alpha, float& l_reg, v8i32& p8) {
; #pragma unroll
;   for (int r = 0; r < 16; ++r) { p0[r] = __builtin_amdgcn_exp2f(p0[r]); p1[r] = __builtin_amdgcn_exp2f(p1[r]); }
;   float ps = 0;
; #pragma unroll
;   for (int r = 0; r < 16; ++r) ps += p0[r];
; #pragma unroll
;   for (int r = 0; r < 16; ++r) ps += p1[r];
;   { auto rr = __builtin_amdgcn_permlane32_swap(__float_as_uint(ps), __float_as_uint(ps), false, false);
;     ps = __uint_as_float(rr[0]) + __uint_as_float(rr[1]); }
;   l_reg = l_reg * alpha + ps;
; #pragma unroll
;   for (int g = 0; g < 4; ++g) {
;     int w = __builtin_amdgcn_cvt_pk_fp8_f32(p0[4 * g], p0[4 * g + 1], 0, false); p8[g] = __builtin_amdgcn_cvt_pk_fp8_f32(p0[4 * g + 2], p0[4 * g + 3], w, true);
;     int u = __builtin_amdgcn_cvt_pk_fp8_f32(p1[4 * g], p1[4 * g + 1], 0, false); p8[4 + g] = __builtin_amdgcn_cvt_pk_fp8_f32(p1[4 * g + 2], p1[4 * g + 3], u, true); }
; }
; __device__ __forceinline__ void pv8(f32x16* o, const char* Vt, const v8i32 p8, int r32, int hi) {
;   const int sw = (r32 >> 2) & 3, a0 = r32 * 64 + (((hi * 2) ^ sw) << 4), a1 = r32 * 64 + (((hi * 2 + 1) ^ sw) << 4);
; #pragma unroll
;   for (int d0 = 0; d0 < 4; ++d0) {
;     const v8i32 vf = cat8(*reinterpret_cast<const v4i32*>(Vt + d0 * 2048 + a0), *reinterpret_cast<const v4i32*>(Vt + d0 * 2048 + a1));
;     o[d0] = __builtin_amdgcn_mfma_scale_f32_32x32x64_f8f6f4(p8, vf, o[d0], 0, 0, 0, 127, 0, 127); }
; }
; __device__ __forceinline__ void qkt9(f32x16& p0, f32x16& p1, const char* Kn, const char* Kr, const v8i32* qf, const float init, int r32, int hi) {
; #pragma unroll
;   for (int r = 0; r < 16; ++r) { p0[r] = init; p1[r] = init; }
; #pragma unroll
;   for (int s = 0; s < 2; ++s) { const int c0 = s * 4 + hi * 2;
;     const v8i32 a0 = cat8(*reinterpret_cast<const v4i32*>(Kn + KN8SW(r32, c0)), *reinterpret_cast<const v4i32*>(Kn + KN8SW(r32, c0 + 1)));
;     const v8i32 a1 = cat8(*reinterpret_cast<const v4i32*>(Kn + 4096 + KN8SW(r32, c0)), *reinterpret_cast<const v4i32*>(Kn + 4096 + KN8SW(r32, c0 + 1)));
;     p0 = __builtin_amdgcn_mfma_scale_f32_32x32x64_f8f6f4(a0, qf[s], p0, 0, 0, 0, 127, 0, 124);
;     p1 = __builtin_amdgcn_mfma_scale_f32_32x32x64_f8f6f4(a1, qf[s], p1, 0, 0, 0, 127, 0, 124); }
;   { const int c0 = hi * 2;
.Lmla_s0_cont:
	ds_read_b128 v[82:85], v215 offset:51200
	ds_read_b128 v[86:89], v216 offset:51200
	ds_read_b128 v[222:225], v215 offset:55296
	ds_read_b128 v[226:229], v216 offset:55296
	v_exp_f32_e32 v0, v114
	v_exp_f32_e32 v177, v115
	v_exp_f32_e32 v179, v116
	v_exp_f32_e32 v254, v117
	v_add_f32_e32 v219, v0, v177
	v_cvt_pk_fp8_f32 v246, v0, v177
	v_add_f32_e32 v219, v179, v219
	v_add_f32_e32 v219, v254, v219
	v_cvt_pk_fp8_f32 v246, v179, v254 op_sel:[0,0,1]
	s_waitcnt lgkmcnt(2)
	v_mfma_scale_f32_32x32x64_f8f6f4 v[82:97], v[82:89], v[146:153], v[230:245], v194, v193 op_sel_hi:[0,0,0]
	v_exp_f32_e32 v0, v118
	v_exp_f32_e32 v177, v119
	v_exp_f32_e32 v179, v120
	v_exp_f32_e32 v254, v121
	v_add_f32_e32 v219, v0, v219
	v_add_f32_e32 v219, v177, v219
	v_cvt_pk_fp8_f32 v247, v0, v177
	v_add_f32_e32 v219, v179, v219
	v_add_f32_e32 v219, v254, v219
	v_cvt_pk_fp8_f32 v247, v179, v254 op_sel:[0,0,1]
	ds_read_b128 v[114:117], v213 offset:51200
	ds_read_b128 v[118:121], v214 offset:51200
	s_waitcnt lgkmcnt(2)
	v_mfma_scale_f32_32x32x64_f8f6f4 v[66:81], v[222:229], v[146:153], v[230:245], v194, v193 op_sel_hi:[0,0,0]
	ds_read_b128 v[222:225], v213 offset:55296
	ds_read_b128 v[226:229], v214 offset:55296
	v_exp_f32_e32 v0, v122
	v_exp_f32_e32 v177, v123
	v_exp_f32_e32 v179, v124
	v_exp_f32_e32 v254, v125
	v_add_f32_e32 v219, v0, v219
	v_add_f32_e32 v219, v177, v219
	v_cvt_pk_fp8_f32 v248, v0, v177
	v_add_f32_e32 v219, v179, v219
	v_add_f32_e32 v219, v254, v219
	v_cvt_pk_fp8_f32 v248, v179, v254 op_sel:[0,0,1]
	v_exp_f32_e32 v0, v126
	v_exp_f32_e32 v177, v127
	v_exp_f32_e32 v179, v128
	v_exp_f32_e32 v254, v129
	v_add_f32_e32 v219, v0, v219
	v_add_f32_e32 v219, v177, v219
	v_cvt_pk_fp8_f32 v249, v0, v177
	v_add_f32_e32 v219, v179, v219
	v_add_f32_e32 v219, v254, v219
	v_cvt_pk_fp8_f32 v249, v179, v254 op_sel:[0,0,1]
	ds_read_b128 v[122:125], v185 offset:59392
	ds_read_b128 v[126:129], v186 offset:59392
	s_waitcnt lgkmcnt(4)
	v_mfma_scale_f32_32x32x64_f8f6f4 v[82:97], v[114:121], v[138:145], v[82:97], v194, v193 op_sel_hi:[0,0,0]
	v_exp_f32_e32 v0, v98
	v_exp_f32_e32 v177, v99
	v_exp_f32_e32 v179, v100
	v_exp_f32_e32 v254, v101
	v_add_f32_e32 v219, v0, v219
	v_add_f32_e32 v219, v177, v219
	v_cvt_pk_fp8_f32 v250, v0, v177
	v_add_f32_e32 v219, v179, v219
	v_add_f32_e32 v219, v254, v219
	v_cvt_pk_fp8_f32 v250, v179, v254 op_sel:[0,0,1]
	s_waitcnt lgkmcnt(2)
	v_mfma_scale_f32_32x32x64_f8f6f4 v[66:81], v[222:229], v[138:145], v[66:81], v194, v193 op_sel_hi:[0,0,0]
	ds_read_b128 v[222:225], v185 offset:61440
	ds_read_b128 v[226:229], v186 offset:61440
	v_exp_f32_e32 v0, v102
	v_exp_f32_e32 v177, v103
	v_exp_f32_e32 v179, v104
	v_exp_f32_e32 v254, v105
	v_add_f32_e32 v219, v0, v219
	v_add_f32_e32 v219, v177, v219
	v_cvt_pk_fp8_f32 v251, v0, v177
	v_add_f32_e32 v219, v179, v219
	v_add_f32_e32 v219, v254, v219
	v_cvt_pk_fp8_f32 v251, v179, v254 op_sel:[0,0,1]
	v_exp_f32_e32 v0, v106
	v_exp_f32_e32 v177, v107
	v_exp_f32_e32 v179, v108
	v_exp_f32_e32 v254, v109
	v_add_f32_e32 v219, v0, v219
	v_add_f32_e32 v219, v177, v219
	v_cvt_pk_fp8_f32 v252, v0, v177
	v_add_f32_e32 v219, v179, v219
	v_add_f32_e32 v219, v254, v219
	v_cvt_pk_fp8_f32 v252, v179, v254 op_sel:[0,0,1]
	s_waitcnt lgkmcnt(2)
	v_mfma_scale_f32_32x32x64_f8f6f4 v[82:97], v[122:129], v[130:137], v[82:97], v194, v193 op_sel_hi:[0,0,0]
	v_exp_f32_e32 v0, v110
	v_exp_f32_e32 v177, v111
	v_exp_f32_e32 v179, v112
	v_exp_f32_e32 v254, v113
	v_add_f32_e32 v219, v0, v219
	v_add_f32_e32 v219, v177, v219
	v_cvt_pk_fp8_f32 v253, v0, v177
	v_add_f32_e32 v219, v179, v219
	v_add_f32_e32 v219, v254, v219
	v_cvt_pk_fp8_f32 v253, v179, v254 op_sel:[0,0,1]
	ds_read_b128 v[122:125], v185 offset:8192
	ds_read_b128 v[126:129], v186 offset:8192
	ds_read_b128 v[114:117], v185 offset:10240
	ds_read_b128 v[118:121], v186 offset:10240
	ds_read_b128 v[106:109], v185 offset:12288
	ds_read_b128 v[110:113], v186 offset:12288
	ds_read_b128 v[98:101], v185 offset:14336
	ds_read_b128 v[102:105], v186 offset:14336
	s_waitcnt lgkmcnt(8)
	v_mfma_scale_f32_32x32x64_f8f6f4 v[66:81], v[222:229], v[130:137], v[66:81], v194, v193 op_sel_hi:[0,0,0]
	v_mov_b32_e32 v0, v219
	s_nop 1
	v_permlane32_swap_b32_e32 v219, v0
	v_add_f32_e32 v219, v219, v0
	v_fma_f32 v209, v209, v221, v219
	s_waitcnt vmcnt(0)
	ds_write_b128 v210, v[158:161]
	ds_write_b128 v211, v[162:165] offset:16384
	s_waitcnt lgkmcnt(0)
	s_barrier
	global_load_dwordx4 v[158:161], v176, s[18:19]
	global_load_dwordx4 v[162:165], v178, s[16:17]
	v_add_u32_e32 v176, 0x2000, v176
	v_add_u32_e32 v178, 0x20000, v178
	v_max_f32_e32 v177, v82, v83
	v_max3_f32 v177, v177, v84, v85
	v_max3_f32 v177, v177, v86, v87
	v_max3_f32 v177, v177, v88, v89
	v_max3_f32 v177, v177, v90, v91
	v_max3_f32 v177, v177, v92, v93
	v_max3_f32 v177, v177, v94, v95
	v_max3_f32 v177, v177, v96, v97
	s_waitcnt lgkmcnt(6)
	v_mfma_scale_f32_32x32x64_f8f6f4 v[50:65], v[246:253], v[122:129], v[50:65], v194, v194 op_sel_hi:[0,0,0]
	v_max_f32_e32 v0, v66, v67
	v_max3_f32 v0, v0, v68, v69
	v_max3_f32 v0, v0, v70, v71
	s_waitcnt lgkmcnt(4)
	v_mfma_scale_f32_32x32x64_f8f6f4 v[34:49], v[246:253], v[114:121], v[34:49], v194, v194 op_sel_hi:[0,0,0]
	v_max3_f32 v0, v0, v72, v73
	v_max3_f32 v0, v0, v74, v75
	v_max3_f32 v0, v0, v76, v77
	s_waitcnt lgkmcnt(2)
	v_mfma_scale_f32_32x32x64_f8f6f4 v[18:33], v[246:253], v[106:113], v[18:33], v194, v194 op_sel_hi:[0,0,0]
	v_max3_f32 v0, v0, v78, v79
	v_max3_f32 v0, v0, v80, v81
	v_max_f32_e32 v177, v177, v0
	v_mov_b32_e32 v0, v177
	v_mov_b32_e32 v218, 1.0
	s_waitcnt lgkmcnt(0)
	v_mfma_scale_f32_32x32x64_f8f6f4 v[2:17], v[246:253], v[98:105], v[2:17], v194, v194 op_sel_hi:[0,0,0]
	s_nop 0
	v_permlane32_swap_b32_e32 v177, v0
	v_max_f32_e32 v177, v177, v0
	v_cmp_ge_f32_e32 vcc, s90, v177
	s_cmp_eq_u64 vcc, exec
	s_cbranch_scc0 .Lmla_s1_newmax
; __device__ __forceinline__ void finishSM9(f32x16& p0, f32x16& p1, float alpha, float& l_reg, v8i32& p8) {
; #pragma unroll
;   for (int r = 0; r < 16; ++r) { p0[r] = __builtin_amdgcn_exp2f(p0[r]); p1[r] = __builtin_amdgcn_exp2f(p1[r]); }
;   float ps = 0;
; #pragma unroll
;   for (int r = 0; r < 16; ++r) ps += p0[r];
; #pragma unroll
;   for (int r = 0; r < 16; ++r) ps += p1[r];
;   { auto rr = __builtin_amdgcn_permlane32_swap(__float_as_uint(ps), __float_as_uint(ps), false, false);
;     ps = __uint_as_float(rr[0]) + __uint_as_float(rr[1]); }
;   l_reg = l_reg * alpha + ps;
; #pragma unroll
;   for (int g = 0; g < 4; ++g) {
;     int w = __builtin_amdgcn_cvt_pk_fp8_f32(p0[4 * g], p0[4 * g + 1], 0, false); p8[g] = __builtin_amdgcn_cvt_pk_fp8_f32(p0[4 * g + 2], p0[4 * g + 3], w, true);
;     int u = __builtin_amdgcn_cvt_pk_fp8_f32(p1[4 * g], p1[4 * g + 1], 0, false); p8[4 + g] = __builtin_amdgcn_cvt_pk_fp8_f32(p1[4 * g + 2], p1[4 * g + 3], u, true); }
; }
; __device__ __forceinline__ void pv8(f32x16* o, const char* Vt, const v8i32 p8, int r32, int hi) {
;   const int sw = (r32 >> 2) & 3, a0 = r32 * 64 + (((hi * 2) ^ sw) << 4), a1 = r32 * 64 + (((hi * 2 + 1) ^ sw) << 4);
; #pragma unroll
;   for (int d0 = 0; d0 < 4; ++d0) {
;     const v8i32 vf = cat8(*reinterpret_cast<const v4i32*>(Vt + d0 * 2048 + a0), *reinterpret_cast<const v4i32*>(Vt + d0 * 2048 + a1));
;     o[d0] = __builtin_amdgcn_mfma_scale_f32_32x32x64_f8f6f4(p8, vf, o[d0], 0, 0, 0, 127, 0, 127); }
; }
; __device__ __forceinline__ void qkt9(f32x16& p0, f32x16& p1, const char* Kn, const char* Kr, const v8i32* qf, const float init, int r32, int hi) {
; #pragma unroll
;   for (int r = 0; r < 16; ++r) { p0[r] = init; p1[r] = init; }
; #pragma unroll
;   for (int s = 0; s < 2; ++s) { const int c0 = s * 4 + hi * 2;
;     const v8i32 a0 = cat8(*reinterpret_cast<const v4i32*>(Kn + KN8SW(r32, c0)), *reinterpret_cast<const v4i32*>(Kn + KN8SW(r32, c0 + 1)));
;     const v8i32 a1 = cat8(*reinterpret_cast<const v4i32*>(Kn + 4096 + KN8SW(r32, c0)), *reinterpret_cast<const v4i32*>(Kn + 4096 + KN8SW(r32, c0 + 1)));
;     p0 = __builtin_amdgcn_mfma_scale_f32_32x32x64_f8f6f4(a0, qf[s], p0, 0, 0, 0, 127, 0, 124);
;     p1 = __builtin_amdgcn_mfma_scale_f32_32x32x64_f8f6f4(a1, qf[s], p1, 0, 0, 0, 127, 0, 124); }
;   { const int c0 = hi * 2;
.Lmla_s1_cont:
	ds_read_b128 v[114:117], v215 offset:16384
	ds_read_b128 v[118:121], v216 offset:16384
	ds_read_b128 v[222:225], v215 offset:20480
	ds_read_b128 v[226:229], v216 offset:20480
	v_exp_f32_e32 v0, v82
	v_exp_f32_e32 v177, v83
	v_exp_f32_e32 v179, v84
	v_exp_f32_e32 v254, v85
	v_add_f32_e32 v219, v0, v177
	v_cvt_pk_fp8_f32 v246, v0, v177
	v_add_f32_e32 v219, v179, v219
	v_add_f32_e32 v219, v254, v219
	v_cvt_pk_fp8_f32 v246, v179, v254 op_sel:[0,0,1]
	s_waitcnt lgkmcnt(2)
	v_mfma_scale_f32_32x32x64_f8f6f4 v[114:129], v[114:121], v[146:153], v[230:245], v194, v193 op_sel_hi:[0,0,0]
	v_exp_f32_e32 v0, v86
	v_exp_f32_e32 v177, v87
	v_exp_f32_e32 v179, v88
	v_exp_f32_e32 v254, v89
	v_add_f32_e32 v219, v0, v219
	v_add_f32_e32 v219, v177, v219
	v_cvt_pk_fp8_f32 v247, v0, v177
	v_add_f32_e32 v219, v179, v219
	v_add_f32_e32 v219, v254, v219
	v_cvt_pk_fp8_f32 v247, v179, v254 op_sel:[0,0,1]
	ds_read_b128 v[82:85], v213 offset:16384
	ds_read_b128 v[86:89], v214 offset:16384
	s_waitcnt lgkmcnt(2)
	v_mfma_scale_f32_32x32x64_f8f6f4 v[98:113], v[222:229], v[146:153], v[230:245], v194, v193 op_sel_hi:[0,0,0]
	ds_read_b128 v[222:225], v213 offset:20480
	ds_read_b128 v[226:229], v214 offset:20480
	v_exp_f32_e32 v0, v90
	v_exp_f32_e32 v177, v91
	v_exp_f32_e32 v179, v92
	v_exp_f32_e32 v254, v93
	v_add_f32_e32 v219, v0, v219
	v_add_f32_e32 v219, v177, v219
	v_cvt_pk_fp8_f32 v248, v0, v177
	v_add_f32_e32 v219, v179, v219
	v_add_f32_e32 v219, v254, v219
	v_cvt_pk_fp8_f32 v248, v179, v254 op_sel:[0,0,1]
	v_exp_f32_e32 v0, v94
	v_exp_f32_e32 v177, v95
	v_exp_f32_e32 v179, v96
	v_exp_f32_e32 v254, v97
	v_add_f32_e32 v219, v0, v219
	v_add_f32_e32 v219, v177, v219
	v_cvt_pk_fp8_f32 v249, v0, v177
	v_add_f32_e32 v219, v179, v219
	v_add_f32_e32 v219, v254, v219
	v_cvt_pk_fp8_f32 v249, v179, v254 op_sel:[0,0,1]
	ds_read_b128 v[90:93], v185 offset:32768
	ds_read_b128 v[94:97], v186 offset:32768
	s_waitcnt lgkmcnt(4)
	v_mfma_scale_f32_32x32x64_f8f6f4 v[114:129], v[82:89], v[138:145], v[114:129], v194, v193 op_sel_hi:[0,0,0]
	v_exp_f32_e32 v0, v66
	v_exp_f32_e32 v177, v67
	v_exp_f32_e32 v179, v68
	v_exp_f32_e32 v254, v69
	v_add_f32_e32 v219, v0, v219
	v_add_f32_e32 v219, v177, v219
	v_cvt_pk_fp8_f32 v250, v0, v177
	v_add_f32_e32 v219, v179, v219
	v_add_f32_e32 v219, v254, v219
	v_cvt_pk_fp8_f32 v250, v179, v254 op_sel:[0,0,1]
	s_waitcnt lgkmcnt(2)
	v_mfma_scale_f32_32x32x64_f8f6f4 v[98:113], v[222:229], v[138:145], v[98:113], v194, v193 op_sel_hi:[0,0,0]
	ds_read_b128 v[222:225], v185 offset:34816
	ds_read_b128 v[226:229], v186 offset:34816
	v_exp_f32_e32 v0, v70
	v_exp_f32_e32 v177, v71
	v_exp_f32_e32 v179, v72
	v_exp_f32_e32 v254, v73
	v_add_f32_e32 v219, v0, v219
	v_add_f32_e32 v219, v177, v219
	v_cvt_pk_fp8_f32 v251, v0, v177
	v_add_f32_e32 v219, v179, v219
	v_add_f32_e32 v219, v254, v219
	v_cvt_pk_fp8_f32 v251, v179, v254 op_sel:[0,0,1]
	v_exp_f32_e32 v0, v74
	v_exp_f32_e32 v177, v75
	v_exp_f32_e32 v179, v76
	v_exp_f32_e32 v254, v77
	v_add_f32_e32 v219, v0, v219
	v_add_f32_e32 v219, v177, v219
	v_cvt_pk_fp8_f32 v252, v0, v177
	v_add_f32_e32 v219, v179, v219
	v_add_f32_e32 v219, v254, v219
	v_cvt_pk_fp8_f32 v252, v179, v254 op_sel:[0,0,1]
	s_waitcnt lgkmcnt(2)
	v_mfma_scale_f32_32x32x64_f8f6f4 v[114:129], v[90:97], v[130:137], v[114:129], v194, v193 op_sel_hi:[0,0,0]
	v_exp_f32_e32 v0, v78
	v_exp_f32_e32 v177, v79
	v_exp_f32_e32 v179, v80
	v_exp_f32_e32 v254, v81
	v_add_f32_e32 v219, v0, v219
	v_add_f32_e32 v219, v177, v219
	v_cvt_pk_fp8_f32 v253, v0, v177
	v_add_f32_e32 v219, v179, v219
	v_add_f32_e32 v219, v254, v219
	v_cvt_pk_fp8_f32 v253, v179, v254 op_sel:[0,0,1]
	ds_read_b128 v[90:93], v185 offset:43008
	ds_read_b128 v[94:97], v186 offset:43008
	ds_read_b128 v[82:85], v185 offset:45056
	ds_read_b128 v[86:89], v186 offset:45056
	ds_read_b128 v[74:77], v185 offset:47104
	ds_read_b128 v[78:81], v186 offset:47104
	ds_read_b128 v[66:69], v185 offset:49152
	ds_read_b128 v[70:73], v186 offset:49152
	s_waitcnt lgkmcnt(8)
	v_mfma_scale_f32_32x32x64_f8f6f4 v[98:113], v[222:229], v[130:137], v[98:113], v194, v193 op_sel_hi:[0,0,0]
	v_mov_b32_e32 v0, v219
	s_nop 1
	v_permlane32_swap_b32_e32 v219, v0
	v_add_f32_e32 v219, v219, v0
	v_fma_f32 v209, v209, v218, v219
	s_waitcnt vmcnt(0)
	ds_write_b128 v210, v[158:161] offset:8192
	ds_write_b128 v211, v[162:165] offset:24576
	s_waitcnt lgkmcnt(0)
	s_barrier
	global_load_dwordx4 v[158:161], v176, s[18:19]
	global_load_dwordx4 v[162:165], v178, s[16:17]
	v_add_u32_e32 v176, 0x2000, v176
	v_add_u32_e32 v178, 0x20000, v178
	v_max_f32_e32 v177, v114, v115
	v_max3_f32 v177, v177, v116, v117
	v_max3_f32 v177, v177, v118, v119
	v_max3_f32 v177, v177, v120, v121
	v_max3_f32 v177, v177, v122, v123
	v_max3_f32 v177, v177, v124, v125
	v_max3_f32 v177, v177, v126, v127
	v_max3_f32 v177, v177, v128, v129
	s_waitcnt lgkmcnt(6)
	v_mfma_scale_f32_32x32x64_f8f6f4 v[50:65], v[246:253], v[90:97], v[50:65], v194, v194 op_sel_hi:[0,0,0]
	v_max_f32_e32 v0, v98, v99
	v_max3_f32 v0, v0, v100, v101
	v_max3_f32 v0, v0, v102, v103
	s_waitcnt lgkmcnt(4)
	v_mfma_scale_f32_32x32x64_f8f6f4 v[34:49], v[246:253], v[82:89], v[34:49], v194, v194 op_sel_hi:[0,0,0]
	v_max3_f32 v0, v0, v104, v105
	v_max3_f32 v0, v0, v106, v107
	v_max3_f32 v0, v0, v108, v109
	s_waitcnt lgkmcnt(2)
	v_mfma_scale_f32_32x32x64_f8f6f4 v[18:33], v[246:253], v[74:81], v[18:33], v194, v194 op_sel_hi:[0,0,0]
	v_max3_f32 v0, v0, v110, v111
	v_max3_f32 v0, v0, v112, v113
	v_max_f32_e32 v177, v177, v0
	v_mov_b32_e32 v0, v177
	v_mov_b32_e32 v221, 1.0
	s_waitcnt lgkmcnt(0)
	v_mfma_scale_f32_32x32x64_f8f6f4 v[2:17], v[246:253], v[66:73], v[2:17], v194, v194 op_sel_hi:[0,0,0]
	s_nop 0
	v_permlane32_swap_b32_e32 v177, v0
	v_max_f32_e32 v177, v177, v0
	v_cmp_ge_f32_e32 vcc, s90, v177
	s_cmp_eq_u64 vcc, exec
	s_cbranch_scc0 .Lmla_s2_newmax
; __device__ __forceinline__ void finishSM9(f32x16& p0, f32x16& p1, float alpha, float& l_reg, v8i32& p8) {
; #pragma unroll
;   for (int r = 0; r < 16; ++r) { p0[r] = __builtin_amdgcn_exp2f(p0[r]); p1[r] = __builtin_amdgcn_exp2f(p1[r]); }
;   float ps = 0;
; #pragma unroll
;   for (int r = 0; r < 16; ++r) ps += p0[r];
; #pragma unroll
;   for (int r = 0; r < 16; ++r) ps += p1[r];
;   { auto rr = __builtin_amdgcn_permlane32_swap(__float_as_uint(ps), __float_as_uint(ps), false, false);
;     ps = __uint_as_float(rr[0]) + __uint_as_float(rr[1]); }
;   l_reg = l_reg * alpha + ps;
; #pragma unroll
;   for (int g = 0; g < 4; ++g) {
;     int w = __builtin_amdgcn_cvt_pk_fp8_f32(p0[4 * g], p0[4 * g + 1], 0, false); p8[g] = __builtin_amdgcn_cvt_pk_fp8_f32(p0[4 * g + 2], p0[4 * g + 3], w, true);
;     int u = __builtin_amdgcn_cvt_pk_fp8_f32(p1[4 * g], p1[4 * g + 1], 0, false); p8[4 + g] = __builtin_amdgcn_cvt_pk_fp8_f32(p1[4 * g + 2], p1[4 * g + 3], u, true); }
; }
; __device__ __forceinline__ void pv8(f32x16* o, const char* Vt, const v8i32 p8, int r32, int hi) {
;   const int sw = (r32 >> 2) & 3, a0 = r32 * 64 + (((hi * 2) ^ sw) << 4), a1 = r32 * 64 + (((hi * 2 + 1) ^ sw) << 4);
; #pragma unroll
;   for (int d0 = 0; d0 < 4; ++d0) {
;     const v8i32 vf = cat8(*reinterpret_cast<const v4i32*>(Vt + d0 * 2048 + a0), *reinterpret_cast<const v4i32*>(Vt + d0 * 2048 + a1));
;     o[d0] = __builtin_amdgcn_mfma_scale_f32_32x32x64_f8f6f4(p8, vf, o[d0], 0, 0, 0, 127, 0, 127); }
; }
; __device__ __forceinline__ void qkt9(f32x16& p0, f32x16& p1, const char* Kn, const char* Kr, const v8i32* qf, const float init, int r32, int hi) {
; #pragma unroll
;   for (int r = 0; r < 16; ++r) { p0[r] = init; p1[r] = init; }
; #pragma unroll
;   for (int s = 0; s < 2; ++s) { const int c0 = s * 4 + hi * 2;
;     const v8i32 a0 = cat8(*reinterpret_cast<const v4i32*>(Kn + KN8SW(r32, c0)), *reinterpret_cast<const v4i32*>(Kn + KN8SW(r32, c0 + 1)));
;     const v8i32 a1 = cat8(*reinterpret_cast<const v4i32*>(Kn + 4096 + KN8SW(r32, c0)), *reinterpret_cast<const v4i32*>(Kn + 4096 + KN8SW(r32, c0 + 1)));
;     p0 = __builtin_amdgcn_mfma_scale_f32_32x32x64_f8f6f4(a0, qf[s], p0, 0, 0, 0, 127, 0, 124);
;     p1 = __builtin_amdgcn_mfma_scale_f32_32x32x64_f8f6f4(a1, qf[s], p1, 0, 0, 0, 127, 0, 124); }
;   { const int c0 = hi * 2;
.Lmla_s2_cont:
	ds_read_b128 v[82:85], v215 offset:24576
	ds_read_b128 v[86:89], v216 offset:24576
	ds_read_b128 v[222:225], v215 offset:28672
	ds_read_b128 v[226:229], v216 offset:28672
	v_exp_f32_e32 v0, v114
	v_exp_f32_e32 v177, v115
	v_exp_f32_e32 v179, v116
	v_exp_f32_e32 v254, v117
	v_add_f32_e32 v219, v0, v177
	v_cvt_pk_fp8_f32 v246, v0, v177
	v_add_f32_e32 v219, v179, v219
	v_add_f32_e32 v219, v254, v219
	v_cvt_pk_fp8_f32 v246, v179, v254 op_sel:[0,0,1]
	s_waitcnt lgkmcnt(2)
	v_mfma_scale_f32_32x32x64_f8f6f4 v[82:97], v[82:89], v[146:153], v[230:245], v194, v193 op_sel_hi:[0,0,0]
	v_exp_f32_e32 v0, v118
	v_exp_f32_e32 v177, v119
	v_exp_f32_e32 v179, v120
	v_exp_f32_e32 v254, v121
	v_add_f32_e32 v219, v0, v219
	v_add_f32_e32 v219, v177, v219
	v_cvt_pk_fp8_f32 v247, v0, v177
	v_add_f32_e32 v219, v179, v219
	v_add_f32_e32 v219, v254, v219
	v_cvt_pk_fp8_f32 v247, v179, v254 op_sel:[0,0,1]
	ds_read_b128 v[114:117], v213 offset:24576
	ds_read_b128 v[118:121], v214 offset:24576
	s_waitcnt lgkmcnt(2)
	v_mfma_scale_f32_32x32x64_f8f6f4 v[66:81], v[222:229], v[146:153], v[230:245], v194, v193 op_sel_hi:[0,0,0]
	ds_read_b128 v[222:225], v213 offset:28672
	ds_read_b128 v[226:229], v214 offset:28672
	v_exp_f32_e32 v0, v122
	v_exp_f32_e32 v177, v123
	v_exp_f32_e32 v179, v124
	v_exp_f32_e32 v254, v125
	v_add_f32_e32 v219, v0, v219
	v_add_f32_e32 v219, v177, v219
	v_cvt_pk_fp8_f32 v248, v0, v177
	v_add_f32_e32 v219, v179, v219
	v_add_f32_e32 v219, v254, v219
	v_cvt_pk_fp8_f32 v248, v179, v254 op_sel:[0,0,1]
	v_exp_f32_e32 v0, v126
	v_exp_f32_e32 v177, v127
	v_exp_f32_e32 v179, v128
	v_exp_f32_e32 v254, v129
	v_add_f32_e32 v219, v0, v219
	v_add_f32_e32 v219, v177, v219
	v_cvt_pk_fp8_f32 v249, v0, v177
	v_add_f32_e32 v219, v179, v219
	v_add_f32_e32 v219, v254, v219
	v_cvt_pk_fp8_f32 v249, v179, v254 op_sel:[0,0,1]
	ds_read_b128 v[122:125], v185 offset:36864
	ds_read_b128 v[126:129], v186 offset:36864
	s_waitcnt lgkmcnt(4)
	v_mfma_scale_f32_32x32x64_f8f6f4 v[82:97], v[114:121], v[138:145], v[82:97], v194, v193 op_sel_hi:[0,0,0]
	v_exp_f32_e32 v0, v98
	v_exp_f32_e32 v177, v99
	v_exp_f32_e32 v179, v100
	v_exp_f32_e32 v254, v101
	v_add_f32_e32 v219, v0, v219
	v_add_f32_e32 v219, v177, v219
	v_cvt_pk_fp8_f32 v250, v0, v177
	v_add_f32_e32 v219, v179, v219
	v_add_f32_e32 v219, v254, v219
	v_cvt_pk_fp8_f32 v250, v179, v254 op_sel:[0,0,1]
	s_waitcnt lgkmcnt(2)
	v_mfma_scale_f32_32x32x64_f8f6f4 v[66:81], v[222:229], v[138:145], v[66:81], v194, v193 op_sel_hi:[0,0,0]
	ds_read_b128 v[222:225], v185 offset:38912
	ds_read_b128 v[226:229], v186 offset:38912
	v_exp_f32_e32 v0, v102
	v_exp_f32_e32 v177, v103
	v_exp_f32_e32 v179, v104
	v_exp_f32_e32 v254, v105
	v_add_f32_e32 v219, v0, v219
	v_add_f32_e32 v219, v177, v219
	v_cvt_pk_fp8_f32 v251, v0, v177
	v_add_f32_e32 v219, v179, v219
	v_add_f32_e32 v219, v254, v219
	v_cvt_pk_fp8_f32 v251, v179, v254 op_sel:[0,0,1]
	v_exp_f32_e32 v0, v106
	v_exp_f32_e32 v177, v107
	v_exp_f32_e32 v179, v108
	v_exp_f32_e32 v254, v109
	v_add_f32_e32 v219, v0, v219
	v_add_f32_e32 v219, v177, v219
	v_cvt_pk_fp8_f32 v252, v0, v177
	v_add_f32_e32 v219, v179, v219
	v_add_f32_e32 v219, v254, v219
	v_cvt_pk_fp8_f32 v252, v179, v254 op_sel:[0,0,1]
	s_waitcnt lgkmcnt(2)
	v_mfma_scale_f32_32x32x64_f8f6f4 v[82:97], v[122:129], v[130:137], v[82:97], v194, v193 op_sel_hi:[0,0,0]
	v_exp_f32_e32 v0, v110
	v_exp_f32_e32 v177, v111
	v_exp_f32_e32 v179, v112
	v_exp_f32_e32 v254, v113
	v_add_f32_e32 v219, v0, v219
	v_add_f32_e32 v219, v177, v219
	v_cvt_pk_fp8_f32 v253, v0, v177
	v_add_f32_e32 v219, v179, v219
	v_add_f32_e32 v219, v254, v219
	v_cvt_pk_fp8_f32 v253, v179, v254 op_sel:[0,0,1]
	ds_read_b128 v[122:125], v185 offset:0
	ds_read_b128 v[126:129], v186 offset:0
	ds_read_b128 v[114:117], v185 offset:2048
	ds_read_b128 v[118:121], v186 offset:2048
	ds_read_b128 v[106:109], v185 offset:4096
	ds_read_b128 v[110:113], v186 offset:4096
	ds_read_b128 v[98:101], v185 offset:6144
	ds_read_b128 v[102:105], v186 offset:6144
	s_waitcnt lgkmcnt(8)
	v_mfma_scale_f32_32x32x64_f8f6f4 v[66:81], v[222:229], v[130:137], v[66:81], v194, v193 op_sel_hi:[0,0,0]
	v_mov_b32_e32 v0, v219
	s_nop 1
	v_permlane32_swap_b32_e32 v219, v0
	v_add_f32_e32 v219, v219, v0
	v_fma_f32 v209, v209, v221, v219
	s_waitcnt vmcnt(0)
	ds_write_b128 v210, v[158:161] offset:43008
	ds_write_b128 v211, v[162:165] offset:51200
	s_waitcnt lgkmcnt(0)
	s_barrier
	global_load_dwordx4 v[158:161], v176, s[18:19]
	global_load_dwordx4 v[162:165], v178, s[16:17]
	v_add_u32_e32 v176, 0x2000, v176
	v_add_u32_e32 v178, 0x20000, v178
	v_max_f32_e32 v177, v82, v83
	v_max3_f32 v177, v177, v84, v85
	v_max3_f32 v177, v177, v86, v87
	v_max3_f32 v177, v177, v88, v89
	v_max3_f32 v177, v177, v90, v91
	v_max3_f32 v177, v177, v92, v93
	v_max3_f32 v177, v177, v94, v95
	v_max3_f32 v177, v177, v96, v97
	s_waitcnt lgkmcnt(6)
	v_mfma_scale_f32_32x32x64_f8f6f4 v[50:65], v[246:253], v[122:129], v[50:65], v194, v194 op_sel_hi:[0,0,0]
	v_max_f32_e32 v0, v66, v67
	v_max3_f32 v0, v0, v68, v69
	v_max3_f32 v0, v0, v70, v71
	s_waitcnt lgkmcnt(4)
	v_mfma_scale_f32_32x32x64_f8f6f4 v[34:49], v[246:253], v[114:121], v[34:49], v194, v194 op_sel_hi:[0,0,0]
	v_max3_f32 v0, v0, v72, v73
	v_max3_f32 v0, v0, v74, v75
	v_max3_f32 v0, v0, v76, v77
	s_waitcnt lgkmcnt(2)
	v_mfma_scale_f32_32x32x64_f8f6f4 v[18:33], v[246:253], v[106:113], v[18:33], v194, v194 op_sel_hi:[0,0,0]
	v_max3_f32 v0, v0, v78, v79
	v_max3_f32 v0, v0, v80, v81
	v_max_f32_e32 v177, v177, v0
	v_mov_b32_e32 v0, v177
	v_mov_b32_e32 v218, 1.0
	s_waitcnt lgkmcnt(0)
	v_mfma_scale_f32_32x32x64_f8f6f4 v[2:17], v[246:253], v[98:105], v[2:17], v194, v194 op_sel_hi:[0,0,0]
	s_nop 0
	v_permlane32_swap_b32_e32 v177, v0
	v_max_f32_e32 v177, v177, v0
	v_cmp_ge_f32_e32 vcc, s90, v177
	s_cmp_eq_u64 vcc, exec
	s_cbranch_scc0 .Lmla_s3_newmax
; __device__ __forceinline__ void finishSM9(f32x16& p0, f32x16& p1, float alpha, float& l_reg, v8i32& p8) {
; #pragma unroll
;   for (int r = 0; r < 16; ++r) { p0[r] = __builtin_amdgcn_exp2f(p0[r]); p1[r] = __builtin_amdgcn_exp2f(p1[r]); }
;   float ps = 0;
; #pragma unroll
;   for (int r = 0; r < 16; ++r) ps += p0[r];
; #pragma unroll
;   for (int r = 0; r < 16; ++r) ps += p1[r];
;   { auto rr = __builtin_amdgcn_permlane32_swap(__float_as_uint(ps), __float_as_uint(ps), false, false);
;     ps = __uint_as_float(rr[0]) + __uint_as_float(rr[1]); }
;   l_reg = l_reg * alpha + ps;
; #pragma unroll
;   for (int g = 0; g < 4; ++g) {
;     int w = __builtin_amdgcn_cvt_pk_fp8_f32(p0[4 * g], p0[4 * g + 1], 0, false); p8[g] = __builtin_amdgcn_cvt_pk_fp8_f32(p0[4 * g + 2], p0[4 * g + 3], w, true);
;     int u = __builtin_amdgcn_cvt_pk_fp8_f32(p1[4 * g], p1[4 * g + 1], 0, false); p8[4 + g] = __builtin_amdgcn_cvt_pk_fp8_f32(p1[4 * g + 2], p1[4 * g + 3], u, true); }
; }
; __device__ __forceinline__ void pv8(f32x16* o, const char* Vt, const v8i32 p8, int r32, int hi) {
;   const int sw = (r32 >> 2) & 3, a0 = r32 * 64 + (((hi * 2) ^ sw) << 4), a1 = r32 * 64 + (((hi * 2 + 1) ^ sw) << 4);
; #pragma unroll
;   for (int d0 = 0; d0 < 4; ++d0) {
;     const v8i32 vf = cat8(*reinterpret_cast<const v4i32*>(Vt + d0 * 2048 + a0), *reinterpret_cast<const v4i32*>(Vt + d0 * 2048 + a1));
;     o[d0] = __builtin_amdgcn_mfma_scale_f32_32x32x64_f8f6f4(p8, vf, o[d0], 0, 0, 0, 127, 0, 127); }
; }
; __device__ __forceinline__ void qkt9(f32x16& p0, f32x16& p1, const char* Kn, const char* Kr, const v8i32* qf, const float init, int r32, int hi) {
; #pragma unroll
;   for (int r = 0; r < 16; ++r) { p0[r] = init; p1[r] = init; }
; #pragma unroll
;   for (int s = 0; s < 2; ++s) { const int c0 = s * 4 + hi * 2;
;     const v8i32 a0 = cat8(*reinterpret_cast<const v4i32*>(Kn + KN8SW(r32, c0)), *reinterpret_cast<const v4i32*>(Kn + KN8SW(r32, c0 + 1)));
;     const v8i32 a1 = cat8(*reinterpret_cast<const v4i32*>(Kn + 4096 + KN8SW(r32, c0)), *reinterpret_cast<const v4i32*>(Kn + 4096 + KN8SW(r32, c0 + 1)));
;     p0 = __builtin_amdgcn_mfma_scale_f32_32x32x64_f8f6f4(a0, qf[s], p0, 0, 0, 0, 127, 0, 124);
;     p1 = __builtin_amdgcn_mfma_scale_f32_32x32x64_f8f6f4(a1, qf[s], p1, 0, 0, 0, 127, 0, 124); }
;   { const int c0 = hi * 2;
.Lmla_s3_cont:
	ds_read_b128 v[114:117], v215 offset:51200
	ds_read_b128 v[118:121], v216 offset:51200
	ds_read_b128 v[222:225], v215 offset:55296
	ds_read_b128 v[226:229], v216 offset:55296
	v_exp_f32_e32 v0, v82
	v_exp_f32_e32 v177, v83
	v_exp_f32_e32 v179, v84
	v_exp_f32_e32 v254, v85
	v_add_f32_e32 v219, v0, v177
	v_cvt_pk_fp8_f32 v246, v0, v177
	v_add_f32_e32 v219, v179, v219
	v_add_f32_e32 v219, v254, v219
	v_cvt_pk_fp8_f32 v246, v179, v254 op_sel:[0,0,1]
	s_waitcnt lgkmcnt(2)
	v_mfma_scale_f32_32x32x64_f8f6f4 v[114:129], v[114:121], v[146:153], v[230:245], v194, v193 op_sel_hi:[0,0,0]
	v_exp_f32_e32 v0, v86
	v_exp_f32_e32 v177, v87
	v_exp_f32_e32 v179, v88
	v_exp_f32_e32 v254, v89
	v_add_f32_e32 v219, v0, v219
	v_add_f32_e32 v219, v177, v219
	v_cvt_pk_fp8_f32 v247, v0, v177
	v_add_f32_e32 v219, v179, v219
	v_add_f32_e32 v219, v254, v219
	v_cvt_pk_fp8_f32 v247, v179, v254 op_sel:[0,0,1]
	ds_read_b128 v[82:85], v213 offset:51200
	ds_read_b128 v[86:89], v214 offset:51200
	s_waitcnt lgkmcnt(2)
	v_mfma_scale_f32_32x32x64_f8f6f4 v[98:113], v[222:229], v[146:153], v[230:245], v194, v193 op_sel_hi:[0,0,0]
	ds_read_b128 v[222:225], v213 offset:55296
	ds_read_b128 v[226:229], v214 offset:55296
	v_exp_f32_e32 v0, v90
	v_exp_f32_e32 v177, v91
	v_exp_f32_e32 v179, v92
	v_exp_f32_e32 v254, v93
	v_add_f32_e32 v219, v0, v219
	v_add_f32_e32 v219, v177, v219
	v_cvt_pk_fp8_f32 v248, v0, v177
	v_add_f32_e32 v219, v179, v219
	v_add_f32_e32 v219, v254, v219
	v_cvt_pk_fp8_f32 v248, v179, v254 op_sel:[0,0,1]
	v_exp_f32_e32 v0, v94
	v_exp_f32_e32 v177, v95
	v_exp_f32_e32 v179, v96
	v_exp_f32_e32 v254, v97
	v_add_f32_e32 v219, v0, v219
	v_add_f32_e32 v219, v177, v219
	v_cvt_pk_fp8_f32 v249, v0, v177
	v_add_f32_e32 v219, v179, v219
	v_add_f32_e32 v219, v254, v219
	v_cvt_pk_fp8_f32 v249, v179, v254 op_sel:[0,0,1]
	ds_read_b128 v[90:93], v185 offset:59392
	ds_read_b128 v[94:97], v186 offset:59392
	s_waitcnt lgkmcnt(4)
	v_mfma_scale_f32_32x32x64_f8f6f4 v[114:129], v[82:89], v[138:145], v[114:129], v194, v193 op_sel_hi:[0,0,0]
	v_exp_f32_e32 v0, v66
	v_exp_f32_e32 v177, v67
	v_exp_f32_e32 v179, v68
	v_exp_f32_e32 v254, v69
	v_add_f32_e32 v219, v0, v219
	v_add_f32_e32 v219, v177, v219
	v_cvt_pk_fp8_f32 v250, v0, v177
	v_add_f32_e32 v219, v179, v219
	v_add_f32_e32 v219, v254, v219
	v_cvt_pk_fp8_f32 v250, v179, v254 op_sel:[0,0,1]
	s_waitcnt lgkmcnt(2)
	v_mfma_scale_f32_32x32x64_f8f6f4 v[98:113], v[222:229], v[138:145], v[98:113], v194, v193 op_sel_hi:[0,0,0]
	ds_read_b128 v[222:225], v185 offset:61440
	ds_read_b128 v[226:229], v186 offset:61440
	v_exp_f32_e32 v0, v70
	v_exp_f32_e32 v177, v71
	v_exp_f32_e32 v179, v72
	v_exp_f32_e32 v254, v73
	v_add_f32_e32 v219, v0, v219
	v_add_f32_e32 v219, v177, v219
	v_cvt_pk_fp8_f32 v251, v0, v177
	v_add_f32_e32 v219, v179, v219
	v_add_f32_e32 v219, v254, v219
	v_cvt_pk_fp8_f32 v251, v179, v254 op_sel:[0,0,1]
	v_exp_f32_e32 v0, v74
	v_exp_f32_e32 v177, v75
	v_exp_f32_e32 v179, v76
	v_exp_f32_e32 v254, v77
	v_add_f32_e32 v219, v0, v219
	v_add_f32_e32 v219, v177, v219
	v_cvt_pk_fp8_f32 v252, v0, v177
	v_add_f32_e32 v219, v179, v219
	v_add_f32_e32 v219, v254, v219
	v_cvt_pk_fp8_f32 v252, v179, v254 op_sel:[0,0,1]
	s_waitcnt lgkmcnt(2)
	v_mfma_scale_f32_32x32x64_f8f6f4 v[114:129], v[90:97], v[130:137], v[114:129], v194, v193 op_sel_hi:[0,0,0]
	v_exp_f32_e32 v0, v78
	v_exp_f32_e32 v177, v79
	v_exp_f32_e32 v179, v80
	v_exp_f32_e32 v254, v81
	v_add_f32_e32 v219, v0, v219
	v_add_f32_e32 v219, v177, v219
	v_cvt_pk_fp8_f32 v253, v0, v177
	v_add_f32_e32 v219, v179, v219
	v_add_f32_e32 v219, v254, v219
	v_cvt_pk_fp8_f32 v253, v179, v254 op_sel:[0,0,1]
	ds_read_b128 v[90:93], v185 offset:8192
	ds_read_b128 v[94:97], v186 offset:8192
	ds_read_b128 v[82:85], v185 offset:10240
	ds_read_b128 v[86:89], v186 offset:10240
	ds_read_b128 v[74:77], v185 offset:12288
	ds_read_b128 v[78:81], v186 offset:12288
	ds_read_b128 v[66:69], v185 offset:14336
	ds_read_b128 v[70:73], v186 offset:14336
	s_waitcnt lgkmcnt(8)
	v_mfma_scale_f32_32x32x64_f8f6f4 v[98:113], v[222:229], v[130:137], v[98:113], v194, v193 op_sel_hi:[0,0,0]
	v_mov_b32_e32 v0, v219
	s_nop 1
	v_permlane32_swap_b32_e32 v219, v0
	v_add_f32_e32 v219, v219, v0
	v_fma_f32 v209, v209, v218, v219
	s_waitcnt vmcnt(0)
	ds_write_b128 v210, v[158:161]
	ds_write_b128 v211, v[162:165] offset:16384
	s_waitcnt lgkmcnt(0)
	s_barrier
	global_load_dwordx4 v[158:161], v176, s[18:19]
	global_load_dwordx4 v[162:165], v178, s[16:17]
	v_add_u32_e32 v176, 0x2000, v176
	v_add_u32_e32 v178, 0x20000, v178
	v_max_f32_e32 v177, v114, v115
	v_max3_f32 v177, v177, v116, v117
	v_max3_f32 v177, v177, v118, v119
	v_max3_f32 v177, v177, v120, v121
	v_max3_f32 v177, v177, v122, v123
	v_max3_f32 v177, v177, v124, v125
	v_max3_f32 v177, v177, v126, v127
	v_max3_f32 v177, v177, v128, v129
	s_waitcnt lgkmcnt(6)
	v_mfma_scale_f32_32x32x64_f8f6f4 v[50:65], v[246:253], v[90:97], v[50:65], v194, v194 op_sel_hi:[0,0,0]
	v_max_f32_e32 v0, v98, v99
	v_max3_f32 v0, v0, v100, v101
	v_max3_f32 v0, v0, v102, v103
	s_waitcnt lgkmcnt(4)
	v_mfma_scale_f32_32x32x64_f8f6f4 v[34:49], v[246:253], v[82:89], v[34:49], v194, v194 op_sel_hi:[0,0,0]
	v_max3_f32 v0, v0, v104, v105
	v_max3_f32 v0, v0, v106, v107
	v_max3_f32 v0, v0, v108, v109
	s_waitcnt lgkmcnt(2)
	v_mfma_scale_f32_32x32x64_f8f6f4 v[18:33], v[246:253], v[74:81], v[18:33], v194, v194 op_sel_hi:[0,0,0]
	v_max3_f32 v0, v0, v110, v111
	v_max3_f32 v0, v0, v112, v113
	v_max_f32_e32 v177, v177, v0
	v_mov_b32_e32 v0, v177
	v_mov_b32_e32 v221, 1.0
	s_waitcnt lgkmcnt(0)
	v_mfma_scale_f32_32x32x64_f8f6f4 v[2:17], v[246:253], v[66:73], v[2:17], v194, v194 op_sel_hi:[0,0,0]
	s_nop 0
	v_permlane32_swap_b32_e32 v177, v0
	v_max_f32_e32 v177, v177, v0
	v_cmp_ge_f32_e32 vcc, s90, v177
	s_cmp_eq_u64 vcc, exec
	s_cbranch_scc0 .Lmla_s4_newmax
; __device__ __forceinline__ void finishSM9(f32x16& p0, f32x16& p1, float alpha, float& l_reg, v8i32& p8) {
; #pragma unroll
;   for (int r = 0; r < 16; ++r) { p0[r] = __builtin_amdgcn_exp2f(p0[r]); p1[r] = __builtin_amdgcn_exp2f(p1[r]); }
;   float ps = 0;
; #pragma unroll
;   for (int r = 0; r < 16; ++r) ps += p0[r];
; #pragma unroll
;   for (int r = 0; r < 16; ++r) ps += p1[r];
;   { auto rr = __builtin_amdgcn_permlane32_swap(__float_as_uint(ps), __float_as_uint(ps), false, false);
;     ps = __uint_as_float(rr[0]) + __uint_as_float(rr[1]); }
;   l_reg = l_reg * alpha + ps;
; #pragma unroll
;   for (int g = 0; g < 4; ++g) {
;     int w = __builtin_amdgcn_cvt_pk_fp8_f32(p0[4 * g], p0[4 * g + 1], 0, false); p8[g] = __builtin_amdgcn_cvt_pk_fp8_f32(p0[4 * g + 2], p0[4 * g + 3], w, true);
;     int u = __builtin_amdgcn_cvt_pk_fp8_f32(p1[4 * g], p1[4 * g + 1], 0, false); p8[4 + g] = __builtin_amdgcn_cvt_pk_fp8_f32(p1[4 * g + 2], p1[4 * g + 3], u, true); }
; }
; __device__ __forceinline__ void pv8(f32x16* o, const char* Vt, const v8i32 p8, int r32, int hi) {
;   const int sw = (r32 >> 2) & 3, a0 = r32 * 64 + (((hi * 2) ^ sw) << 4), a1 = r32 * 64 + (((hi * 2 + 1) ^ sw) << 4);
; #pragma unroll
;   for (int d0 = 0; d0 < 4; ++d0) {
;     const v8i32 vf = cat8(*reinterpret_cast<const v4i32*>(Vt + d0 * 2048 + a0), *reinterpret_cast<const v4i32*>(Vt + d0 * 2048 + a1));
;     o[d0] = __builtin_amdgcn_mfma_scale_f32_32x32x64_f8f6f4(p8, vf, o[d0], 0, 0, 0, 127, 0, 127); }
; }
; __device__ __forceinline__ void qkt9(f32x16& p0, f32x16& p1, const char* Kn, const char* Kr, const v8i32* qf, const float init, int r32, int hi) {
; #pragma unroll
;   for (int r = 0; r < 16; ++r) { p0[r] = init; p1[r] = init; }
; #pragma unroll
;   for (int s = 0; s < 2; ++s) { const int c0 = s * 4 + hi * 2;
;     const v8i32 a0 = cat8(*reinterpret_cast<const v4i32*>(Kn + KN8SW(r32, c0)), *reinterpret_cast<const v4i32*>(Kn + KN8SW(r32, c0 + 1)));
;     const v8i32 a1 = cat8(*reinterpret_cast<const v4i32*>(Kn + 4096 + KN8SW(r32, c0)), *reinterpret_cast<const v4i32*>(Kn + 4096 + KN8SW(r32, c0 + 1)));
;     p0 = __builtin_amdgcn_mfma_scale_f32_32x32x64_f8f6f4(a0, qf[s], p0, 0, 0, 0, 127, 0, 124);
;     p1 = __builtin_amdgcn_mfma_scale_f32_32x32x64_f8f6f4(a1, qf[s], p1, 0, 0, 0, 127, 0, 124); }
;   { const int c0 = hi * 2;
.Lmla_s4_cont:
	ds_read_b128 v[82:85], v215 offset:16384
	ds_read_b128 v[86:89], v216 offset:16384
	ds_read_b128 v[222:225], v215 offset:20480
	ds_read_b128 v[226:229], v216 offset:20480
	v_exp_f32_e32 v0, v114
	v_exp_f32_e32 v177, v115
	v_exp_f32_e32 v179, v116
	v_exp_f32_e32 v254, v117
	v_add_f32_e32 v219, v0, v177
	v_cvt_pk_fp8_f32 v246, v0, v177
	v_add_f32_e32 v219, v179, v219
	v_add_f32_e32 v219, v254, v219
	v_cvt_pk_fp8_f32 v246, v179, v254 op_sel:[0,0,1]
	s_waitcnt lgkmcnt(2)
	v_mfma_scale_f32_32x32x64_f8f6f4 v[82:97], v[82:89], v[146:153], v[230:245], v194, v193 op_sel_hi:[0,0,0]
	v_exp_f32_e32 v0, v118
	v_exp_f32_e32 v177, v119
	v_exp_f32_e32 v179, v120
	v_exp_f32_e32 v254, v121
	v_add_f32_e32 v219, v0, v219
	v_add_f32_e32 v219, v177, v219
	v_cvt_pk_fp8_f32 v247, v0, v177
	v_add_f32_e32 v219, v179, v219
	v_add_f32_e32 v219, v254, v219
	v_cvt_pk_fp8_f32 v247, v179, v254 op_sel:[0,0,1]
	ds_read_b128 v[114:117], v213 offset:16384
	ds_read_b128 v[118:121], v214 offset:16384
	s_waitcnt lgkmcnt(2)
	v_mfma_scale_f32_32x32x64_f8f6f4 v[66:81], v[222:229], v[146:153], v[230:245], v194, v193 op_sel_hi:[0,0,0]
	ds_read_b128 v[222:225], v213 offset:20480
	ds_read_b128 v[226:229], v214 offset:20480
	v_exp_f32_e32 v0, v122
	v_exp_f32_e32 v177, v123
	v_exp_f32_e32 v179, v124
	v_exp_f32_e32 v254, v125
	v_add_f32_e32 v219, v0, v219
	v_add_f32_e32 v219, v177, v219
	v_cvt_pk_fp8_f32 v248, v0, v177
	v_add_f32_e32 v219, v179, v219
	v_add_f32_e32 v219, v254, v219
	v_cvt_pk_fp8_f32 v248, v179, v254 op_sel:[0,0,1]
	v_exp_f32_e32 v0, v126
	v_exp_f32_e32 v177, v127
	v_exp_f32_e32 v179, v128
	v_exp_f32_e32 v254, v129
	v_add_f32_e32 v219, v0, v219
	v_add_f32_e32 v219, v177, v219
	v_cvt_pk_fp8_f32 v249, v0, v177
	v_add_f32_e32 v219, v179, v219
	v_add_f32_e32 v219, v254, v219
	v_cvt_pk_fp8_f32 v249, v179, v254 op_sel:[0,0,1]
	ds_read_b128 v[122:125], v185 offset:32768
	ds_read_b128 v[126:129], v186 offset:32768
	s_waitcnt lgkmcnt(4)
	v_mfma_scale_f32_32x32x64_f8f6f4 v[82:97], v[114:121], v[138:145], v[82:97], v194, v193 op_sel_hi:[0,0,0]
	v_exp_f32_e32 v0, v98
	v_exp_f32_e32 v177, v99
	v_exp_f32_e32 v179, v100
	v_exp_f32_e32 v254, v101
	v_add_f32_e32 v219, v0, v219
	v_add_f32_e32 v219, v177, v219
	v_cvt_pk_fp8_f32 v250, v0, v177
	v_add_f32_e32 v219, v179, v219
	v_add_f32_e32 v219, v254, v219
	v_cvt_pk_fp8_f32 v250, v179, v254 op_sel:[0,0,1]
	s_waitcnt lgkmcnt(2)
	v_mfma_scale_f32_32x32x64_f8f6f4 v[66:81], v[222:229], v[138:145], v[66:81], v194, v193 op_sel_hi:[0,0,0]
	ds_read_b128 v[222:225], v185 offset:34816
	ds_read_b128 v[226:229], v186 offset:34816
	v_exp_f32_e32 v0, v102
	v_exp_f32_e32 v177, v103
	v_exp_f32_e32 v179, v104
	v_exp_f32_e32 v254, v105
	v_add_f32_e32 v219, v0, v219
	v_add_f32_e32 v219, v177, v219
	v_cvt_pk_fp8_f32 v251, v0, v177
	v_add_f32_e32 v219, v179, v219
	v_add_f32_e32 v219, v254, v219
	v_cvt_pk_fp8_f32 v251, v179, v254 op_sel:[0,0,1]
	v_exp_f32_e32 v0, v106
	v_exp_f32_e32 v177, v107
	v_exp_f32_e32 v179, v108
	v_exp_f32_e32 v254, v109
	v_add_f32_e32 v219, v0, v219
	v_add_f32_e32 v219, v177, v219
	v_cvt_pk_fp8_f32 v252, v0, v177
	v_add_f32_e32 v219, v179, v219
	v_add_f32_e32 v219, v254, v219
	v_cvt_pk_fp8_f32 v252, v179, v254 op_sel:[0,0,1]
	s_waitcnt lgkmcnt(2)
	v_mfma_scale_f32_32x32x64_f8f6f4 v[82:97], v[122:129], v[130:137], v[82:97], v194, v193 op_sel_hi:[0,0,0]
	v_exp_f32_e32 v0, v110
	v_exp_f32_e32 v177, v111
	v_exp_f32_e32 v179, v112
	v_exp_f32_e32 v254, v113
	v_add_f32_e32 v219, v0, v219
	v_add_f32_e32 v219, v177, v219
	v_cvt_pk_fp8_f32 v253, v0, v177
	v_add_f32_e32 v219, v179, v219
	v_add_f32_e32 v219, v254, v219
	v_cvt_pk_fp8_f32 v253, v179, v254 op_sel:[0,0,1]
	ds_read_b128 v[122:125], v185 offset:43008
	ds_read_b128 v[126:129], v186 offset:43008
	ds_read_b128 v[114:117], v185 offset:45056
	ds_read_b128 v[118:121], v186 offset:45056
	ds_read_b128 v[106:109], v185 offset:47104
	ds_read_b128 v[110:113], v186 offset:47104
	ds_read_b128 v[98:101], v185 offset:49152
	ds_read_b128 v[102:105], v186 offset:49152
	s_waitcnt lgkmcnt(8)
	v_mfma_scale_f32_32x32x64_f8f6f4 v[66:81], v[222:229], v[130:137], v[66:81], v194, v193 op_sel_hi:[0,0,0]
	v_mov_b32_e32 v0, v219
	s_nop 1
	v_permlane32_swap_b32_e32 v219, v0
	v_add_f32_e32 v219, v219, v0
	v_fma_f32 v209, v209, v221, v219
	s_waitcnt vmcnt(0)
	ds_write_b128 v210, v[158:161] offset:8192
	ds_write_b128 v211, v[162:165] offset:24576
	s_waitcnt lgkmcnt(0)
	s_barrier
	global_load_dwordx4 v[158:161], v176, s[18:19]
	global_load_dwordx4 v[162:165], v178, s[16:17]
	v_add_u32_e32 v176, 0x2000, v176
	v_add_u32_e32 v178, 0x20000, v178
	v_max_f32_e32 v177, v82, v83
	v_max3_f32 v177, v177, v84, v85
	v_max3_f32 v177, v177, v86, v87
	v_max3_f32 v177, v177, v88, v89
	v_max3_f32 v177, v177, v90, v91
	v_max3_f32 v177, v177, v92, v93
	v_max3_f32 v177, v177, v94, v95
	v_max3_f32 v177, v177, v96, v97
	s_waitcnt lgkmcnt(6)
	v_mfma_scale_f32_32x32x64_f8f6f4 v[50:65], v[246:253], v[122:129], v[50:65], v194, v194 op_sel_hi:[0,0,0]
	v_max_f32_e32 v0, v66, v67
	v_max3_f32 v0, v0, v68, v69
	v_max3_f32 v0, v0, v70, v71
	s_waitcnt lgkmcnt(4)
	v_mfma_scale_f32_32x32x64_f8f6f4 v[34:49], v[246:253], v[114:121], v[34:49], v194, v194 op_sel_hi:[0,0,0]
	v_max3_f32 v0, v0, v72, v73
	v_max3_f32 v0, v0, v74, v75
	v_max3_f32 v0, v0, v76, v77
	s_waitcnt lgkmcnt(2)
	v_mfma_scale_f32_32x32x64_f8f6f4 v[18:33], v[246:253], v[106:113], v[18:33], v194, v194 op_sel_hi:[0,0,0]
	v_max3_f32 v0, v0, v78, v79
	v_max3_f32 v0, v0, v80, v81
	v_max_f32_e32 v177, v177, v0
	v_mov_b32_e32 v0, v177
	v_mov_b32_e32 v218, 1.0
	s_waitcnt lgkmcnt(0)
	v_mfma_scale_f32_32x32x64_f8f6f4 v[2:17], v[246:253], v[98:105], v[2:17], v194, v194 op_sel_hi:[0,0,0]
	s_nop 0
	v_permlane32_swap_b32_e32 v177, v0
	v_max_f32_e32 v177, v177, v0
	v_cmp_ge_f32_e32 vcc, s90, v177
	s_cmp_eq_u64 vcc, exec
	s_cbranch_scc0 .Lmla_s5_newmax
; __device__ __forceinline__ void finishSM9(f32x16& p0, f32x16& p1, float alpha, float& l_reg, v8i32& p8) {
; #pragma unroll
;   for (int r = 0; r < 16; ++r) { p0[r] = __builtin_amdgcn_exp2f(p0[r]); p1[r] = __builtin_amdgcn_exp2f(p1[r]); }
;   float ps = 0;
; #pragma unroll
;   for (int r = 0; r < 16; ++r) ps += p0[r];
; #pragma unroll
;   for (int r = 0; r < 16; ++r) ps += p1[r];
;   { auto rr = __builtin_amdgcn_permlane32_swap(__float_as_uint(ps), __float_as_uint(ps), false, false);
;     ps = __uint_as_float(rr[0]) + __uint_as_float(rr[1]); }
;   l_reg = l_reg * alpha + ps;
; #pragma unroll
;   for (int g = 0; g < 4; ++g) {
;     int w = __builtin_amdgcn_cvt_pk_fp8_f32(p0[4 * g], p0[4 * g + 1], 0, false); p8[g] = __builtin_amdgcn_cvt_pk_fp8_f32(p0[4 * g + 2], p0[4 * g + 3], w, true);
;     int u = __builtin_amdgcn_cvt_pk_fp8_f32(p1[4 * g], p1[4 * g + 1], 0, false); p8[4 + g] = __builtin_amdgcn_cvt_pk_fp8_f32(p1[4 * g + 2], p1[4 * g + 3], u, true); }
; }
; __device__ __forceinline__ void pv8(f32x16* o, const char* Vt, const v8i32 p8, int r32, int hi) {
;   const int sw = (r32 >> 2) & 3, a0 = r32 * 64 + (((hi * 2) ^ sw) << 4), a1 = r32 * 64 + (((hi * 2 + 1) ^ sw) << 4);
; #pragma unroll
;   for (int d0 = 0; d0 < 4; ++d0) {
;     const v8i32 vf = cat8(*reinterpret_cast<const v4i32*>(Vt + d0 * 2048 + a0), *reinterpret_cast<const v4i32*>(Vt + d0 * 2048 + a1));
;     o[d0] = __builtin_amdgcn_mfma_scale_f32_32x32x64_f8f6f4(p8, vf, o[d0], 0, 0, 0, 127, 0, 127); }
; }
; __device__ __forceinline__ void qkt9(f32x16& p0, f32x16& p1, const char* Kn, const char* Kr, const v8i32* qf, const float init, int r32, int hi) {
; #pragma unroll
;   for (int r = 0; r < 16; ++r) { p0[r] = init; p1[r] = init; }
; #pragma unroll
;   for (int s = 0; s < 2; ++s) { const int c0 = s * 4 + hi * 2;
;     const v8i32 a0 = cat8(*reinterpret_cast<const v4i32*>(Kn + KN8SW(r32, c0)), *reinterpret_cast<const v4i32*>(Kn + KN8SW(r32, c0 + 1)));
;     const v8i32 a1 = cat8(*reinterpret_cast<const v4i32*>(Kn + 4096 + KN8SW(r32, c0)), *reinterpret_cast<const v4i32*>(Kn + 4096 + KN8SW(r32, c0 + 1)));
;     p0 = __builtin_amdgcn_mfma_scale_f32_32x32x64_f8f6f4(a0, qf[s], p0, 0, 0, 0, 127, 0, 124);
;     p1 = __builtin_amdgcn_mfma_scale_f32_32x32x64_f8f6f4(a1, qf[s], p1, 0, 0, 0, 127, 0, 124); }
;   { const int c0 = hi * 2;
.Lmla_s5_cont:
	s_add_i32 s30, s30, 1
	s_cmpk_lt_u32 s30, 42
	s_cbranch_scc1 .Lmla_stag_loop
	ds_read_b128 v[114:117], v215 offset:24576
	ds_read_b128 v[118:121], v216 offset:24576
	ds_read_b128 v[222:225], v215 offset:28672
	ds_read_b128 v[226:229], v216 offset:28672
	v_exp_f32_e32 v0, v82
	v_exp_f32_e32 v177, v83
	v_exp_f32_e32 v179, v84
	v_exp_f32_e32 v254, v85
	v_add_f32_e32 v219, v0, v177
	v_cvt_pk_fp8_f32 v246, v0, v177
	v_add_f32_e32 v219, v179, v219
	v_add_f32_e32 v219, v254, v219
	v_cvt_pk_fp8_f32 v246, v179, v254 op_sel:[0,0,1]
	s_waitcnt lgkmcnt(2)
	v_mfma_scale_f32_32x32x64_f8f6f4 v[114:129], v[114:121], v[146:153], v[230:245], v194, v193 op_sel_hi:[0,0,0]
	v_exp_f32_e32 v0, v86
	v_exp_f32_e32 v177, v87
	v_exp_f32_e32 v179, v88
	v_exp_f32_e32 v254, v89
	v_add_f32_e32 v219, v0, v219
	v_add_f32_e32 v219, v177, v219
	v_cvt_pk_fp8_f32 v247, v0, v177
	v_add_f32_e32 v219, v179, v219
	v_add_f32_e32 v219, v254, v219
	v_cvt_pk_fp8_f32 v247, v179, v254 op_sel:[0,0,1]
	ds_read_b128 v[82:85], v213 offset:24576
	ds_read_b128 v[86:89], v214 offset:24576
	s_waitcnt lgkmcnt(2)
	v_mfma_scale_f32_32x32x64_f8f6f4 v[98:113], v[222:229], v[146:153], v[230:245], v194, v193 op_sel_hi:[0,0,0]
	ds_read_b128 v[222:225], v213 offset:28672
	ds_read_b128 v[226:229], v214 offset:28672
	v_exp_f32_e32 v0, v90
	v_exp_f32_e32 v177, v91
	v_exp_f32_e32 v179, v92
	v_exp_f32_e32 v254, v93
	v_add_f32_e32 v219, v0, v219
	v_add_f32_e32 v219, v177, v219
	v_cvt_pk_fp8_f32 v248, v0, v177
	v_add_f32_e32 v219, v179, v219
	v_add_f32_e32 v219, v254, v219
	v_cvt_pk_fp8_f32 v248, v179, v254 op_sel:[0,0,1]
	v_exp_f32_e32 v0, v94
	v_exp_f32_e32 v177, v95
	v_exp_f32_e32 v179, v96
	v_exp_f32_e32 v254, v97
	v_add_f32_e32 v219, v0, v219
	v_add_f32_e32 v219, v177, v219
	v_cvt_pk_fp8_f32 v249, v0, v177
	v_add_f32_e32 v219, v179, v219
	v_add_f32_e32 v219, v254, v219
	v_cvt_pk_fp8_f32 v249, v179, v254 op_sel:[0,0,1]
	ds_read_b128 v[90:93], v185 offset:36864
	ds_read_b128 v[94:97], v186 offset:36864
	s_waitcnt lgkmcnt(4)
	v_mfma_scale_f32_32x32x64_f8f6f4 v[114:129], v[82:89], v[138:145], v[114:129], v194, v193 op_sel_hi:[0,0,0]
	v_exp_f32_e32 v0, v66
	v_exp_f32_e32 v177, v67
	v_exp_f32_e32 v179, v68
	v_exp_f32_e32 v254, v69
	v_add_f32_e32 v219, v0, v219
	v_add_f32_e32 v219, v177, v219
	v_cvt_pk_fp8_f32 v250, v0, v177
	v_add_f32_e32 v219, v179, v219
	v_add_f32_e32 v219, v254, v219
	v_cvt_pk_fp8_f32 v250, v179, v254 op_sel:[0,0,1]
	s_waitcnt lgkmcnt(2)
	v_mfma_scale_f32_32x32x64_f8f6f4 v[98:113], v[222:229], v[138:145], v[98:113], v194, v193 op_sel_hi:[0,0,0]
	ds_read_b128 v[222:225], v185 offset:38912
	ds_read_b128 v[226:229], v186 offset:38912
	v_exp_f32_e32 v0, v70
	v_exp_f32_e32 v177, v71
	v_exp_f32_e32 v179, v72
	v_exp_f32_e32 v254, v73
	v_add_f32_e32 v219, v0, v219
	v_add_f32_e32 v219, v177, v219
	v_cvt_pk_fp8_f32 v251, v0, v177
	v_add_f32_e32 v219, v179, v219
	v_add_f32_e32 v219, v254, v219
	v_cvt_pk_fp8_f32 v251, v179, v254 op_sel:[0,0,1]
	v_exp_f32_e32 v0, v74
	v_exp_f32_e32 v177, v75
	v_exp_f32_e32 v179, v76
	v_exp_f32_e32 v254, v77
	v_add_f32_e32 v219, v0, v219
	v_add_f32_e32 v219, v177, v219
	v_cvt_pk_fp8_f32 v252, v0, v177
	v_add_f32_e32 v219, v179, v219
	v_add_f32_e32 v219, v254, v219
	v_cvt_pk_fp8_f32 v252, v179, v254 op_sel:[0,0,1]
	s_waitcnt lgkmcnt(2)
	v_mfma_scale_f32_32x32x64_f8f6f4 v[114:129], v[90:97], v[130:137], v[114:129], v194, v193 op_sel_hi:[0,0,0]
	v_exp_f32_e32 v0, v78
	v_exp_f32_e32 v177, v79
	v_exp_f32_e32 v179, v80
	v_exp_f32_e32 v254, v81
	v_add_f32_e32 v219, v0, v219
	v_add_f32_e32 v219, v177, v219
	v_cvt_pk_fp8_f32 v253, v0, v177
	v_add_f32_e32 v219, v179, v219
	v_add_f32_e32 v219, v254, v219
	v_cvt_pk_fp8_f32 v253, v179, v254 op_sel:[0,0,1]
	ds_read_b128 v[90:93], v185 offset:0
	ds_read_b128 v[94:97], v186 offset:0
	ds_read_b128 v[82:85], v185 offset:2048
	ds_read_b128 v[86:89], v186 offset:2048
	ds_read_b128 v[74:77], v185 offset:4096
	ds_read_b128 v[78:81], v186 offset:4096
	ds_read_b128 v[66:69], v185 offset:6144
	ds_read_b128 v[70:73], v186 offset:6144
	s_waitcnt lgkmcnt(8)
	v_mfma_scale_f32_32x32x64_f8f6f4 v[98:113], v[222:229], v[130:137], v[98:113], v194, v193 op_sel_hi:[0,0,0]
	v_mov_b32_e32 v0, v219
	s_nop 1
	v_permlane32_swap_b32_e32 v219, v0
	v_add_f32_e32 v219, v219, v0
	v_fma_f32 v209, v209, v218, v219
	s_waitcnt vmcnt(0)
	ds_write_b128 v210, v[158:161] offset:43008
	ds_write_b128 v211, v[162:165] offset:51200
	s_waitcnt lgkmcnt(0)
	s_barrier
	global_load_dwordx4 v[158:161], v176, s[18:19]
	global_load_dwordx4 v[162:165], v178, s[16:17]
	v_add_u32_e32 v176, 0x2000, v176
	v_add_u32_e32 v178, 0x20000, v178
	v_max_f32_e32 v177, v114, v115
	v_max3_f32 v177, v177, v116, v117
	v_max3_f32 v177, v177, v118, v119
	v_max3_f32 v177, v177, v120, v121
	v_max3_f32 v177, v177, v122, v123
	v_max3_f32 v177, v177, v124, v125
	v_max3_f32 v177, v177, v126, v127
	v_max3_f32 v177, v177, v128, v129
	s_waitcnt lgkmcnt(6)
	v_mfma_scale_f32_32x32x64_f8f6f4 v[50:65], v[246:253], v[90:97], v[50:65], v194, v194 op_sel_hi:[0,0,0]
	v_max_f32_e32 v0, v98, v99
	v_max3_f32 v0, v0, v100, v101
	v_max3_f32 v0, v0, v102, v103
	s_waitcnt lgkmcnt(4)
	v_mfma_scale_f32_32x32x64_f8f6f4 v[34:49], v[246:253], v[82:89], v[34:49], v194, v194 op_sel_hi:[0,0,0]
	v_max3_f32 v0, v0, v104, v105
	v_max3_f32 v0, v0, v106, v107
	v_max3_f32 v0, v0, v108, v109
	s_waitcnt lgkmcnt(2)
	v_mfma_scale_f32_32x32x64_f8f6f4 v[18:33], v[246:253], v[74:81], v[18:33], v194, v194 op_sel_hi:[0,0,0]
	v_max3_f32 v0, v0, v110, v111
	v_max3_f32 v0, v0, v112, v113
	v_max_f32_e32 v177, v177, v0
	v_mov_b32_e32 v0, v177
	v_mov_b32_e32 v221, 1.0
	s_waitcnt lgkmcnt(0)
	v_mfma_scale_f32_32x32x64_f8f6f4 v[2:17], v[246:253], v[66:73], v[2:17], v194, v194 op_sel_hi:[0,0,0]
	s_nop 0
	v_permlane32_swap_b32_e32 v177, v0
	v_max_f32_e32 v177, v177, v0
	v_cmp_ge_f32_e32 vcc, s90, v177
	s_cmp_eq_u64 vcc, exec
	s_cbranch_scc0 .Lmla_q0_newmax
; __device__ __forceinline__ void finishSM9(f32x16& p0, f32x16& p1, float alpha, float& l_reg, v8i32& p8) {
; #pragma unroll
;   for (int r = 0; r < 16; ++r) { p0[r] = __builtin_amdgcn_exp2f(p0[r]); p1[r] = __builtin_amdgcn_exp2f(p1[r]); }
;   float ps = 0;
; #pragma unroll
;   for (int r = 0; r < 16; ++r) ps += p0[r];
; #pragma unroll
;   for (int r = 0; r < 16; ++r) ps += p1[r];
;   { auto rr = __builtin_amdgcn_permlane32_swap(__float_as_uint(ps), __float_as_uint(ps), false, false);
;     ps = __uint_as_float(rr[0]) + __uint_as_float(rr[1]); }
;   l_reg = l_reg * alpha + ps;
; #pragma unroll
;   for (int g = 0; g < 4; ++g) {
;     int w = __builtin_amdgcn_cvt_pk_fp8_f32(p0[4 * g], p0[4 * g + 1], 0, false); p8[g] = __builtin_amdgcn_cvt_pk_fp8_f32(p0[4 * g + 2], p0[4 * g + 3], w, true);
;     int u = __builtin_amdgcn_cvt_pk_fp8_f32(p1[4 * g], p1[4 * g + 1], 0, false); p8[4 + g] = __builtin_amdgcn_cvt_pk_fp8_f32(p1[4 * g + 2], p1[4 * g + 3], u, true); }
; }
; __device__ __forceinline__ void pv8(f32x16* o, const char* Vt, const v8i32 p8, int r32, int hi) {
;   const int sw = (r32 >> 2) & 3, a0 = r32 * 64 + (((hi * 2) ^ sw) << 4), a1 = r32 * 64 + (((hi * 2 + 1) ^ sw) << 4);
; #pragma unroll
;   for (int d0 = 0; d0 < 4; ++d0) {
;     const v8i32 vf = cat8(*reinterpret_cast<const v4i32*>(Vt + d0 * 2048 + a0), *reinterpret_cast<const v4i32*>(Vt + d0 * 2048 + a1));
;     o[d0] = __builtin_amdgcn_mfma_scale_f32_32x32x64_f8f6f4(p8, vf, o[d0], 0, 0, 0, 127, 0, 127); }
; }
; __device__ __forceinline__ void qkt9(f32x16& p0, f32x16& p1, const char* Kn, const char* Kr, const v8i32* qf, const float init, int r32, int hi) {
; #pragma unroll
;   for (int r = 0; r < 16; ++r) { p0[r] = init; p1[r] = init; }
; #pragma unroll
;   for (int s = 0; s < 2; ++s) { const int c0 = s * 4 + hi * 2;
;     const v8i32 a0 = cat8(*reinterpret_cast<const v4i32*>(Kn + KN8SW(r32, c0)), *reinterpret_cast<const v4i32*>(Kn + KN8SW(r32, c0 + 1)));
;     const v8i32 a1 = cat8(*reinterpret_cast<const v4i32*>(Kn + 4096 + KN8SW(r32, c0)), *reinterpret_cast<const v4i32*>(Kn + 4096 + KN8SW(r32, c0 + 1)));
;     p0 = __builtin_amdgcn_mfma_scale_f32_32x32x64_f8f6f4(a0, qf[s], p0, 0, 0, 0, 127, 0, 124);
;     p1 = __builtin_amdgcn_mfma_scale_f32_32x32x64_f8f6f4(a1, qf[s], p1, 0, 0, 0, 127, 0, 124); }
;   { const int c0 = hi * 2;
.Lmla_q0_cont:
	ds_read_b128 v[82:85], v215 offset:51200
	ds_read_b128 v[86:89], v216 offset:51200
	ds_read_b128 v[222:225], v215 offset:55296
	ds_read_b128 v[226:229], v216 offset:55296
	v_exp_f32_e32 v0, v114
	v_exp_f32_e32 v177, v115
	v_exp_f32_e32 v179, v116
	v_exp_f32_e32 v254, v117
	v_add_f32_e32 v219, v0, v177
	v_cvt_pk_fp8_f32 v246, v0, v177
	v_add_f32_e32 v219, v179, v219
	v_add_f32_e32 v219, v254, v219
	v_cvt_pk_fp8_f32 v246, v179, v254 op_sel:[0,0,1]
	s_waitcnt lgkmcnt(2)
	v_mfma_scale_f32_32x32x64_f8f6f4 v[82:97], v[82:89], v[146:153], v[230:245], v194, v193 op_sel_hi:[0,0,0]
	v_exp_f32_e32 v0, v118
	v_exp_f32_e32 v177, v119
	v_exp_f32_e32 v179, v120
	v_exp_f32_e32 v254, v121
	v_add_f32_e32 v219, v0, v219
	v_add_f32_e32 v219, v177, v219
	v_cvt_pk_fp8_f32 v247, v0, v177
	v_add_f32_e32 v219, v179, v219
	v_add_f32_e32 v219, v254, v219
	v_cvt_pk_fp8_f32 v247, v179, v254 op_sel:[0,0,1]
	ds_read_b128 v[114:117], v213 offset:51200
	ds_read_b128 v[118:121], v214 offset:51200
	s_waitcnt lgkmcnt(2)
	v_mfma_scale_f32_32x32x64_f8f6f4 v[66:81], v[222:229], v[146:153], v[230:245], v194, v193 op_sel_hi:[0,0,0]
	ds_read_b128 v[222:225], v213 offset:55296
	ds_read_b128 v[226:229], v214 offset:55296
	v_exp_f32_e32 v0, v122
	v_exp_f32_e32 v177, v123
	v_exp_f32_e32 v179, v124
	v_exp_f32_e32 v254, v125
	v_add_f32_e32 v219, v0, v219
	v_add_f32_e32 v219, v177, v219
	v_cvt_pk_fp8_f32 v248, v0, v177
	v_add_f32_e32 v219, v179, v219
	v_add_f32_e32 v219, v254, v219
	v_cvt_pk_fp8_f32 v248, v179, v254 op_sel:[0,0,1]
	v_exp_f32_e32 v0, v126
	v_exp_f32_e32 v177, v127
	v_exp_f32_e32 v179, v128
	v_exp_f32_e32 v254, v129
	v_add_f32_e32 v219, v0, v219
	v_add_f32_e32 v219, v177, v219
	v_cvt_pk_fp8_f32 v249, v0, v177
	v_add_f32_e32 v219, v179, v219
	v_add_f32_e32 v219, v254, v219
	v_cvt_pk_fp8_f32 v249, v179, v254 op_sel:[0,0,1]
	ds_read_b128 v[122:125], v185 offset:59392
	ds_read_b128 v[126:129], v186 offset:59392
	s_waitcnt lgkmcnt(4)
	v_mfma_scale_f32_32x32x64_f8f6f4 v[82:97], v[114:121], v[138:145], v[82:97], v194, v193 op_sel_hi:[0,0,0]
	v_exp_f32_e32 v0, v98
	v_exp_f32_e32 v177, v99
	v_exp_f32_e32 v179, v100
	v_exp_f32_e32 v254, v101
	v_add_f32_e32 v219, v0, v219
	v_add_f32_e32 v219, v177, v219
	v_cvt_pk_fp8_f32 v250, v0, v177
	v_add_f32_e32 v219, v179, v219
	v_add_f32_e32 v219, v254, v219
	v_cvt_pk_fp8_f32 v250, v179, v254 op_sel:[0,0,1]
	s_waitcnt lgkmcnt(2)
	v_mfma_scale_f32_32x32x64_f8f6f4 v[66:81], v[222:229], v[138:145], v[66:81], v194, v193 op_sel_hi:[0,0,0]
	ds_read_b128 v[222:225], v185 offset:61440
	ds_read_b128 v[226:229], v186 offset:61440
	v_exp_f32_e32 v0, v102
	v_exp_f32_e32 v177, v103
	v_exp_f32_e32 v179, v104
	v_exp_f32_e32 v254, v105
	v_add_f32_e32 v219, v0, v219
	v_add_f32_e32 v219, v177, v219
	v_cvt_pk_fp8_f32 v251, v0, v177
	v_add_f32_e32 v219, v179, v219
	v_add_f32_e32 v219, v254, v219
	v_cvt_pk_fp8_f32 v251, v179, v254 op_sel:[0,0,1]
	v_exp_f32_e32 v0, v106
	v_exp_f32_e32 v177, v107
	v_exp_f32_e32 v179, v108
	v_exp_f32_e32 v254, v109
	v_add_f32_e32 v219, v0, v219
	v_add_f32_e32 v219, v177, v219
	v_cvt_pk_fp8_f32 v252, v0, v177
	v_add_f32_e32 v219, v179, v219
	v_add_f32_e32 v219, v254, v219
	v_cvt_pk_fp8_f32 v252, v179, v254 op_sel:[0,0,1]
	s_waitcnt lgkmcnt(2)
	v_mfma_scale_f32_32x32x64_f8f6f4 v[82:97], v[122:129], v[130:137], v[82:97], v194, v193 op_sel_hi:[0,0,0]
	v_exp_f32_e32 v0, v110
	v_exp_f32_e32 v177, v111
	v_exp_f32_e32 v179, v112
	v_exp_f32_e32 v254, v113
	v_add_f32_e32 v219, v0, v219
	v_add_f32_e32 v219, v177, v219
	v_cvt_pk_fp8_f32 v253, v0, v177
	v_add_f32_e32 v219, v179, v219
	v_add_f32_e32 v219, v254, v219
	v_cvt_pk_fp8_f32 v253, v179, v254 op_sel:[0,0,1]
	ds_read_b128 v[122:125], v185 offset:8192
	ds_read_b128 v[126:129], v186 offset:8192
	ds_read_b128 v[114:117], v185 offset:10240
	ds_read_b128 v[118:121], v186 offset:10240
	ds_read_b128 v[106:109], v185 offset:12288
	ds_read_b128 v[110:113], v186 offset:12288
	ds_read_b128 v[98:101], v185 offset:14336
	ds_read_b128 v[102:105], v186 offset:14336
	s_waitcnt lgkmcnt(8)
	v_mfma_scale_f32_32x32x64_f8f6f4 v[66:81], v[222:229], v[130:137], v[66:81], v194, v193 op_sel_hi:[0,0,0]
	v_mov_b32_e32 v0, v219
	s_nop 1
	v_permlane32_swap_b32_e32 v219, v0
	v_add_f32_e32 v219, v219, v0
	v_fma_f32 v209, v209, v221, v219
	s_waitcnt vmcnt(0)
	ds_write_b128 v210, v[158:161]
	ds_write_b128 v211, v[162:165] offset:16384
	s_waitcnt lgkmcnt(0)
	s_barrier
	v_max_f32_e32 v177, v82, v83
	v_max3_f32 v177, v177, v84, v85
	v_max3_f32 v177, v177, v86, v87
	v_max3_f32 v177, v177, v88, v89
	v_max3_f32 v177, v177, v90, v91
	v_max3_f32 v177, v177, v92, v93
	v_max3_f32 v177, v177, v94, v95
	v_max3_f32 v177, v177, v96, v97
	s_waitcnt lgkmcnt(6)
	v_mfma_scale_f32_32x32x64_f8f6f4 v[50:65], v[246:253], v[122:129], v[50:65], v194, v194 op_sel_hi:[0,0,0]
	v_max_f32_e32 v0, v66, v67
	v_max3_f32 v0, v0, v68, v69
	v_max3_f32 v0, v0, v70, v71
	s_waitcnt lgkmcnt(4)
	v_mfma_scale_f32_32x32x64_f8f6f4 v[34:49], v[246:253], v[114:121], v[34:49], v194, v194 op_sel_hi:[0,0,0]
	v_max3_f32 v0, v0, v72, v73
	v_max3_f32 v0, v0, v74, v75
	v_max3_f32 v0, v0, v76, v77
	s_waitcnt lgkmcnt(2)
	v_mfma_scale_f32_32x32x64_f8f6f4 v[18:33], v[246:253], v[106:113], v[18:33], v194, v194 op_sel_hi:[0,0,0]
	v_max3_f32 v0, v0, v78, v79
	v_max3_f32 v0, v0, v80, v81
	v_max_f32_e32 v177, v177, v0
	v_mov_b32_e32 v0, v177
	v_mov_b32_e32 v218, 1.0
	s_waitcnt lgkmcnt(0)
	v_mfma_scale_f32_32x32x64_f8f6f4 v[2:17], v[246:253], v[98:105], v[2:17], v194, v194 op_sel_hi:[0,0,0]
	s_nop 0
	v_permlane32_swap_b32_e32 v177, v0
	v_max_f32_e32 v177, v177, v0
	v_cmp_ge_f32_e32 vcc, s90, v177
	s_cmp_eq_u64 vcc, exec
	s_cbranch_scc0 .Lmla_q1_newmax
